# byte-neutral stack: queue ds hand-off + permlane32 softmax max exchange + permlane16/32 P1 epilogue sums (all later code at best2 offsets)
# speedup vs baseline: 1.0062x; 1.0007x over previous
; template <int EPI>
; __device__ void gemm8(const bf16* A, const bf16* Bt, const int K, const int ntN, const int ntTot, const EpiArgs ea, char* smem) {
;     ...
;       for (int ai = 0; ai < 2; ++ai)
; #pragma unroll
;         for (int m = 0; m < 4; ++m) {
;           const int row = brow + ai * 128 + wr * 64 + m * 16 + fr;
;           const float rs = ssl[ai * 128 + wr * 64 + m * 16 + fr];
;           float v[2][2][4]; float ss = 0.f;
; #pragma unroll
;           for (int bj = 0; bj < 2; ++bj)
; #pragma unroll
;             for (int n = 0; n < 2; ++n)
; #pragma unroll
;               for (int j = 0; j < 4; ++j) { float x = acc[ai][bj][m][n][j] * rs; v[bj][n][j] = x; ss += x * x; }
;           float rr = 1.f;
;           if (nsel) {
;             ss += __shfl_xor(ss, 16); ss += __shfl_xor(ss, 32);
;             rr = rsqrtf(ss * (1.f / 64.f) + EPS);
;           }
;           int grow = row;
;           if (dperm) {
;             int b = row >> 13, t = row & (SEQ - 1);
;             grow = b * SEQ + (t & ((1 << sh) - 1)) * (SEQ >> sh) + (t >> sh);
;           }
;           bf16* orow = ea.outb + ((size_t)c * NT + grow) * 64 + fq * 8;
; #pragma unroll
;           for (int bj = 0; bj < 2; ++bj) {
;             u32x4 o;
;             o[0] = pack2(v[bj][0][0] * rr * gv[bj][0][0], v[bj][0][1] * rr * gv[bj][0][1]);
;             o[1] = pack2(v[bj][0][2] * rr * gv[bj][0][2], v[bj][0][3] * rr * gv[bj][0][3]);
;             o[2] = pack2(v[bj][1][0] * rr * gv[bj][1][0], v[bj][1][1] * rr * gv[bj][1][1]);
;             o[3] = pack2(v[bj][1][2] * rr * gv[bj][1][2], v[bj][1][3] * rr * gv[bj][1][3]);
;             *(u32x4*)(orow + bj * 32) = o;
;           }
;         }
.LBB0_191:
	s_or_b64 exec, exec, s[2:3]
	v_lshl_add_u64 v[134:135], v[130:131], 0, v[0:1]
	global_load_dwordx4 v[138:141], v[134:135], off offset:16
	global_load_dwordx4 v[142:145], v[134:135], off
	global_load_dwordx4 v[130:133], v[134:135], off offset:144
	s_nop 0
	global_load_dwordx4 v[134:137], v[134:135], off offset:128
	ds_read_b32 v162, v161
	s_xor_b64 s[16:17], s[0:1], -1
	v_mov_b32_e32 v165, 1.0
	v_mov_b32_e32 v175, 1.0
	s_waitcnt lgkmcnt(0)
	v_mul_f32_e32 v174, v118, v162
	v_mul_f32_e32 v173, v119, v162
	v_mul_f32_e32 v172, v120, v162
	v_mul_f32_e32 v171, v121, v162
	v_mul_f32_e32 v170, v114, v162
	v_mul_f32_e32 v169, v115, v162
	v_mul_f32_e32 v168, v116, v162
	v_mul_f32_e32 v167, v117, v162
	v_pk_mul_f32 v[126:127], v[126:127], v[162:163] op_sel_hi:[1,0]
	v_pk_mul_f32 v[120:121], v[128:129], v[162:163] op_sel_hi:[1,0]
	v_pk_mul_f32 v[118:119], v[122:123], v[162:163] op_sel_hi:[1,0]
	v_pk_mul_f32 v[116:117], v[124:125], v[162:163] op_sel_hi:[1,0]
	s_and_saveexec_b64 s[2:3], s[16:17]
	s_cbranch_execz .LBB0_193
	v_mul_f32_e32 v122, v173, v173
	v_fmac_f32_e32 v122, v174, v174
	v_fmac_f32_e32 v122, v172, v172
	v_fmac_f32_e32 v122, v171, v171
	v_fmac_f32_e32 v122, v170, v170
	v_fmac_f32_e32 v122, v169, v169
	v_fmac_f32_e32 v122, v168, v168
	v_fmac_f32_e32 v122, v167, v167
	v_pk_mul_f32 v[114:115], v[126:127], v[126:127]
	s_nop 0
	v_add_f32_e32 v114, v114, v122
	v_add_f32_e32 v122, v115, v114
	v_pk_mul_f32 v[114:115], v[120:121], v[120:121]
	s_nop 0
	v_add_f32_e32 v114, v114, v122
	v_add_f32_e32 v122, v115, v114
	v_pk_mul_f32 v[114:115], v[118:119], v[118:119]
	s_nop 0
	v_add_f32_e32 v114, v114, v122
	v_add_f32_e32 v122, v115, v114
	v_pk_mul_f32 v[114:115], v[116:117], v[116:117]
	s_nop 0
	v_add_f32_e32 v114, v114, v122
	v_and_b32_e32 v122, 64, v229
	v_add_f32_e32 v114, v115, v114
	v_add_u32_e32 v122, 64, v122
	v_mov_b32_e32 v115, v114
	s_nop 1
	v_permlane16_swap_b32_e32 v115, v114
	s_waitcnt lgkmcnt(0)
	v_add_f32_e32 v114, v114, v115
	v_mov_b32_e32 v115, v114
	s_nop 1
	v_permlane32_swap_b32_e32 v115, v114
	s_waitcnt lgkmcnt(0)
	v_add_f32_e32 v114, v114, v115
	v_fmamk_f32 v114, v114, 0x3c800000, v231
	v_mul_f32_e32 v115, 0x4b800000, v114
	v_cmp_gt_f32_e64 s[4:5], s12, v114
	s_nop 1
	v_cndmask_b32_e64 v114, v114, v115, s[4:5]
	v_rsq_f32_e32 v114, v114
	s_nop 0
	v_mul_f32_e32 v115, 0x45800000, v114
	v_cndmask_b32_e64 v175, v114, v115, s[4:5]
	s_branch .LBB0_193
	s_nop 0
	s_nop 0
	s_nop 0
	s_nop 0
	s_nop 0
	s_nop 0
	s_nop 0
	s_nop 0
	s_nop 0
	s_nop 0
	s_nop 0
.LBB0_193:
	s_or_b64 exec, exec, s[2:3]
	v_mul_lo_u16_e32 v114, 0xab, v153
	v_lshrrev_b16_e32 v114, 9, v114
	v_and_b32_e32 v114, 6, v114
	v_add_u16_e32 v114, v153, v114
	v_and_b32_e32 v164, 6, v114
	s_waitcnt vmcnt(0)
	v_cndmask_b32_e64 v114, v142, 1.0, s[0:1]
	v_mul_f32_e32 v162, v166, v114
	v_cndmask_b32_e64 v114, v143, 1.0, s[0:1]
	v_mul_f32_e32 v163, v166, v114
	v_cndmask_b32_e64 v114, v144, 1.0, s[0:1]
	v_mul_f32_e32 v144, v166, v114
	v_cndmask_b32_e64 v114, v145, 1.0, s[0:1]
	v_mul_f32_e32 v145, v166, v114
	v_cndmask_b32_e64 v114, v138, 1.0, s[0:1]
	v_mul_f32_e32 v142, v166, v114
	v_cndmask_b32_e64 v114, v139, 1.0, s[0:1]
	v_mul_f32_e32 v143, v166, v114
	v_cndmask_b32_e64 v114, v140, 1.0, s[0:1]
	v_mul_f32_e32 v138, v166, v114
	v_cndmask_b32_e64 v114, v141, 1.0, s[0:1]
	v_mul_f32_e32 v139, v166, v114
	v_cndmask_b32_e64 v114, v134, 1.0, s[0:1]
	v_mul_f32_e32 v134, v166, v114
	v_cndmask_b32_e64 v114, v135, 1.0, s[0:1]
	v_mul_f32_e32 v135, v166, v114
	v_cndmask_b32_e64 v114, v136, 1.0, s[0:1]
	v_mul_f32_e32 v128, v166, v114
	v_cndmask_b32_e64 v114, v137, 1.0, s[0:1]
	v_mul_f32_e32 v129, v166, v114
	v_cndmask_b32_e64 v114, v130, 1.0, s[0:1]
	v_mul_f32_e32 v140, v174, v175
	v_mul_f32_e32 v141, v173, v175
	v_mul_f32_e32 v124, v166, v114
	v_cndmask_b32_e64 v114, v131, 1.0, s[0:1]
	v_mul_f32_e32 v140, v162, v140
	v_mul_f32_e32 v141, v163, v141
	v_mul_f32_e32 v125, v166, v114
	v_cndmask_b32_e64 v114, v132, 1.0, s[0:1]
	v_cvt_pk_bf16_f32 v176, v140, v141
	v_mul_f32_e32 v140, v172, v175
	v_mul_f32_e32 v141, v171, v175
	v_mul_f32_e32 v122, v166, v114
	v_cndmask_b32_e64 v114, v133, 1.0, s[0:1]
	v_mul_f32_e32 v140, v144, v140
	v_mul_f32_e32 v141, v145, v141
	v_mul_f32_e32 v123, v166, v114
	v_mov_b32_e32 v114, 13
	v_cvt_pk_bf16_f32 v177, v140, v141
	v_mul_f32_e32 v140, v170, v175
	v_mul_f32_e32 v141, v169, v175
	v_sub_u32_sdwa v114, v114, v164 dst_sel:DWORD dst_unused:UNUSED_PAD src0_sel:DWORD src1_sel:WORD_0
	v_cmp_gt_u32_e64 s[40:41], 18, v153
	v_add_u32_e32 v131, s42, v157
	v_mul_f32_e32 v140, v142, v140
	v_mul_f32_e32 v141, v143, v141
	v_cndmask_b32_e64 v130, 13, v114, s[40:41]
	v_or_b32_e32 v133, v131, v156
	v_bitop3_b32 v136, v131, s28, v156 bitop3:0xc8
	v_cvt_pk_bf16_f32 v178, v140, v141
	v_mul_f32_e32 v140, v168, v175
	v_mul_f32_e32 v141, v167, v175
	v_and_b32_e32 v132, 0xffffe000, v131
	v_lshlrev_b32_e32 v137, v130, v133
	v_lshrrev_b32_sdwa v136, v164, v136 dst_sel:DWORD dst_unused:UNUSED_PAD src0_sel:WORD_0 src1_sel:DWORD
	v_mul_f32_e32 v140, v138, v140
	v_mul_f32_e32 v141, v139, v141
	v_and_b32_e32 v137, 0x1ffe, v137
	v_or_b32_e32 v136, v136, v132
	v_cvt_pk_bf16_f32 v179, v140, v141
	ds_read_b32 v140, v161 offset:64
	v_add_u32_e32 v136, v136, v137
	v_ashrrev_i32_e32 v153, 31, v152
	v_cndmask_b32_e64 v136, v133, v136, s[40:41]
	v_lshlrev_b64 v[114:115], 21, v[152:153]
	v_ashrrev_i32_e32 v137, 31, v136
	v_mul_f32_e32 v126, v126, v175
	v_mul_f32_e32 v127, v127, v175
	v_mul_f32_e32 v120, v120, v175
	v_mul_f32_e32 v121, v121, v175
	v_mul_f32_e32 v118, v118, v175
	v_mul_f32_e32 v119, v119, v175
	v_mul_f32_e32 v116, v116, v175
	v_mul_f32_e32 v117, v117, v175
	v_lshl_add_u64 v[114:115], v[148:149], 0, v[114:115]
	v_lshlrev_b64 v[136:137], 7, v[136:137]
	v_mul_f32_e32 v126, v134, v126
	v_mul_f32_e32 v127, v135, v127
	v_mul_f32_e32 v120, v128, v120
	v_mul_f32_e32 v121, v129, v121
	v_mul_f32_e32 v118, v124, v118
	v_mul_f32_e32 v119, v125, v119
	v_mul_f32_e32 v116, v122, v116
	v_mul_f32_e32 v117, v123, v117
	v_lshl_add_u64 v[136:137], v[114:115], 0, v[136:137]
	v_cvt_pk_bf16_f32 v166, v126, v127
	v_cvt_pk_bf16_f32 v167, v120, v121
	v_cvt_pk_bf16_f32 v168, v118, v119
	v_cvt_pk_bf16_f32 v169, v116, v117
	s_waitcnt lgkmcnt(0)
	v_mul_f32_e32 v127, v102, v140
	v_mul_f32_e32 v126, v103, v140
	v_mul_f32_e32 v121, v104, v140
	v_mul_f32_e32 v120, v105, v140
	v_mul_f32_e32 v119, v98, v140
	v_mul_f32_e32 v118, v99, v140
	v_mul_f32_e32 v117, v100, v140
	v_mul_f32_e32 v116, v101, v140
	v_pk_mul_f32 v[104:105], v[110:111], v[140:141] op_sel_hi:[1,0]
	v_pk_mul_f32 v[102:103], v[112:113], v[140:141] op_sel_hi:[1,0]
	v_pk_mul_f32 v[100:101], v[106:107], v[140:141] op_sel_hi:[1,0]
	v_pk_mul_f32 v[98:99], v[108:109], v[140:141] op_sel_hi:[1,0]
	global_store_dwordx4 v[136:137], v[176:179], off
	global_store_dwordx4 v[136:137], v[166:169], off offset:64
	s_and_saveexec_b64 s[0:1], s[16:17]
	s_cbranch_execz .LBB0_195
; template <int EPI>
; __device__ void gemm8(const bf16* A, const bf16* Bt, const int K, const int ntN, const int ntTot, const EpiArgs ea, char* smem) {
;     ...
;               for (int j = 0; j < 4; ++j) { float x = acc[ai][bj][m][n][j] * rs; v[bj][n][j] = x; ss += x * x; }
;           float rr = 1.f;
;           if (nsel) {
;             ss += __shfl_xor(ss, 16); ss += __shfl_xor(ss, 32);
;             rr = rsqrtf(ss * (1.f / 64.f) + EPS);
;           }
;           int grow = row;
;           if (dperm) {
;             int b = row >> 13, t = row & (SEQ - 1);
;             grow = b * SEQ + (t & ((1 << sh) - 1)) * (SEQ >> sh) + (t >> sh);
;           }
;           bf16* orow = ea.outb + ((size_t)c * NT + grow) * 64 + fq * 8;
; #pragma unroll
;           for (int bj = 0; bj < 2; ++bj) {
;             u32x4 o;
;             o[0] = pack2(v[bj][0][0] * rr * gv[bj][0][0], v[bj][0][1] * rr * gv[bj][0][1]);
;             o[1] = pack2(v[bj][0][2] * rr * gv[bj][0][2], v[bj][0][3] * rr * gv[bj][0][3]);
;             o[2] = pack2(v[bj][1][0] * rr * gv[bj][1][0], v[bj][1][1] * rr * gv[bj][1][1]);
;             o[3] = pack2(v[bj][1][2] * rr * gv[bj][1][2], v[bj][1][3] * rr * gv[bj][1][3]);
;             *(u32x4*)(orow + bj * 32) = o;
	v_mul_f32_e32 v108, v126, v126
	v_fmac_f32_e32 v108, v127, v127
	v_fmac_f32_e32 v108, v121, v121
	v_fmac_f32_e32 v108, v120, v120
	v_fmac_f32_e32 v108, v119, v119
	v_fmac_f32_e32 v108, v118, v118
	v_fmac_f32_e32 v108, v117, v117
	v_fmac_f32_e32 v108, v116, v116
	v_pk_mul_f32 v[106:107], v[104:105], v[104:105]
	s_nop 0
	v_add_f32_e32 v106, v106, v108
	v_add_f32_e32 v108, v107, v106
	v_pk_mul_f32 v[106:107], v[102:103], v[102:103]
	s_nop 0
	v_add_f32_e32 v106, v106, v108
	v_add_f32_e32 v108, v107, v106
	v_pk_mul_f32 v[106:107], v[100:101], v[100:101]
	s_nop 0
	v_add_f32_e32 v106, v106, v108
	v_add_f32_e32 v108, v107, v106
	v_pk_mul_f32 v[106:107], v[98:99], v[98:99]
	s_nop 0
	v_add_f32_e32 v106, v106, v108
	v_and_b32_e32 v108, 64, v229
	v_add_f32_e32 v106, v107, v106
	v_add_u32_e32 v108, 64, v108
	v_mov_b32_e32 v107, v106
	s_nop 1
	v_permlane16_swap_b32_e32 v107, v106
	s_waitcnt lgkmcnt(0)
	v_add_f32_e32 v106, v106, v107
	v_mov_b32_e32 v107, v106
	s_nop 1
	v_permlane32_swap_b32_e32 v107, v106
	s_waitcnt lgkmcnt(0)
	v_add_f32_e32 v106, v106, v107
	v_fmamk_f32 v106, v106, 0x3c800000, v231
	v_mul_f32_e32 v107, 0x4b800000, v106
	v_cmp_gt_f32_e64 s[4:5], s12, v106
	s_nop 1
	v_cndmask_b32_e64 v106, v106, v107, s[4:5]
	v_rsq_f32_e32 v106, v106
	s_nop 0
	v_mul_f32_e32 v107, 0x45800000, v106
	v_cndmask_b32_e64 v165, v106, v107, s[4:5]
	s_branch .LBB0_195
	s_nop 0
	s_nop 0
	s_nop 0
	s_nop 0
	s_nop 0
	s_nop 0
	s_nop 0
	s_nop 0
	s_nop 0
	s_nop 0
	s_nop 0
.LBB0_195:
	s_or_b64 exec, exec, s[0:1]
	v_or_b32_e32 v106, 16, v133
	v_bitop3_b32 v107, v133, s29, 16 bitop3:0xc8
	v_lshlrev_b32_e32 v108, v130, v106
	v_lshrrev_b32_sdwa v107, v164, v107 dst_sel:DWORD dst_unused:UNUSED_PAD src0_sel:WORD_0 src1_sel:DWORD
	v_and_b32_e32 v108, 0x1ffe, v108
	v_or_b32_e32 v107, v107, v132
	v_add_u32_e32 v107, v107, v108
	v_cndmask_b32_e64 v106, v106, v107, s[40:41]
	v_ashrrev_i32_e32 v107, 31, v106
	v_lshlrev_b64 v[106:107], 7, v[106:107]
	v_lshl_add_u64 v[110:111], v[114:115], 0, v[106:107]
	v_mul_f32_e32 v106, v127, v165
	v_mul_f32_e32 v107, v126, v165
	v_mul_f32_e32 v106, v162, v106
	v_mul_f32_e32 v107, v163, v107
	v_cvt_pk_bf16_f32 v106, v106, v107
	v_mul_f32_e32 v107, v121, v165
	v_mul_f32_e32 v108, v120, v165
	v_mul_f32_e32 v107, v144, v107
	v_mul_f32_e32 v108, v145, v108
	v_cvt_pk_bf16_f32 v107, v107, v108
	v_mul_f32_e32 v108, v119, v165
	v_mul_f32_e32 v109, v118, v165
	v_mul_f32_e32 v108, v142, v108
	v_mul_f32_e32 v109, v143, v109
	v_cvt_pk_bf16_f32 v108, v108, v109
	v_mul_f32_e32 v109, v117, v165
	v_mul_f32_e32 v112, v116, v165
	v_mul_f32_e32 v109, v138, v109
	v_mul_f32_e32 v112, v139, v112
	v_cvt_pk_bf16_f32 v109, v109, v112
	global_store_dwordx4 v[110:111], v[106:109], off
	ds_read_b32 v108, v161 offset:128
	v_mul_f32_e32 v104, v104, v165
	v_mul_f32_e32 v105, v105, v165
	v_mul_f32_e32 v102, v102, v165
	v_mul_f32_e32 v103, v103, v165
	v_mul_f32_e32 v100, v100, v165
	v_mul_f32_e32 v101, v101, v165
	v_mul_f32_e32 v98, v98, v165
	v_mul_f32_e32 v99, v99, v165
	v_mul_f32_e32 v104, v134, v104
	v_mul_f32_e32 v105, v135, v105
	v_mul_f32_e32 v102, v128, v102
	v_mul_f32_e32 v103, v129, v103
	v_mul_f32_e32 v100, v124, v100
	v_mul_f32_e32 v101, v125, v101
	v_mul_f32_e32 v98, v122, v98
	v_mul_f32_e32 v99, v123, v99
	v_cvt_pk_bf16_f32 v104, v104, v105
	v_cvt_pk_bf16_f32 v105, v102, v103
	v_cvt_pk_bf16_f32 v106, v100, v101
	v_cvt_pk_bf16_f32 v107, v98, v99
	global_store_dwordx4 v[110:111], v[104:107], off offset:64
	s_waitcnt lgkmcnt(0)
	v_mul_f32_e32 v103, v88, v108
	v_mul_f32_e32 v102, v89, v108
	v_mul_f32_e32 v105, v86, v108
	v_mul_f32_e32 v104, v87, v108
	v_mul_f32_e32 v101, v82, v108
	v_mul_f32_e32 v100, v83, v108
	v_mul_f32_e32 v99, v84, v108
	v_mul_f32_e32 v98, v85, v108
	v_pk_mul_f32 v[88:89], v[94:95], v[108:109] op_sel_hi:[1,0]
	v_pk_mul_f32 v[86:87], v[96:97], v[108:109] op_sel_hi:[1,0]
	v_pk_mul_f32 v[84:85], v[90:91], v[108:109] op_sel_hi:[1,0]
	v_pk_mul_f32 v[82:83], v[92:93], v[108:109] op_sel_hi:[1,0]
	v_mov_b32_e32 v90, 1.0
	v_mov_b32_e32 v91, 1.0
	s_and_saveexec_b64 s[0:1], s[16:17]
	s_cbranch_execz .LBB0_197
	v_mul_f32_e32 v91, v104, v104
	v_fmac_f32_e32 v91, v105, v105
	v_fmac_f32_e32 v91, v103, v103
	v_fmac_f32_e32 v91, v102, v102
	v_fmac_f32_e32 v91, v101, v101
	v_fmac_f32_e32 v91, v100, v100
	v_fmac_f32_e32 v91, v99, v99
	v_fmac_f32_e32 v91, v98, v98
	v_pk_mul_f32 v[92:93], v[88:89], v[88:89]
	s_nop 0
	v_add_f32_e32 v91, v92, v91
	v_add_f32_e32 v91, v93, v91
	v_pk_mul_f32 v[92:93], v[86:87], v[86:87]
	s_nop 0
	v_add_f32_e32 v91, v92, v91
	v_add_f32_e32 v91, v93, v91
	v_pk_mul_f32 v[92:93], v[84:85], v[84:85]
	s_nop 0
	v_add_f32_e32 v91, v92, v91
	v_add_f32_e32 v91, v93, v91
	v_pk_mul_f32 v[92:93], v[82:83], v[82:83]
	s_nop 0
	v_add_f32_e32 v91, v92, v91
	v_add_f32_e32 v91, v93, v91
	v_and_b32_e32 v93, 64, v229
	v_add_u32_e32 v93, 64, v93
	v_mov_b32_e32 v92, v91
	s_nop 1
	v_permlane16_swap_b32_e32 v92, v91
	s_waitcnt lgkmcnt(0)
	v_add_f32_e32 v91, v91, v92
	v_mov_b32_e32 v92, v91
	s_nop 1
	v_permlane32_swap_b32_e32 v92, v91
	s_waitcnt lgkmcnt(0)
	v_add_f32_e32 v91, v91, v92
	v_fmamk_f32 v91, v91, 0x3c800000, v231
	v_mul_f32_e32 v92, 0x4b800000, v91
	v_cmp_gt_f32_e64 s[4:5], s12, v91
	s_nop 1
	v_cndmask_b32_e64 v91, v91, v92, s[4:5]
	v_rsq_f32_e32 v91, v91
	s_nop 0
	v_mul_f32_e32 v92, 0x45800000, v91
	v_cndmask_b32_e64 v91, v91, v92, s[4:5]
	s_branch .LBB0_197
	s_nop 0
	s_nop 0
	s_nop 0
	s_nop 0
	s_nop 0
	s_nop 0
	s_nop 0
	s_nop 0
	s_nop 0
	s_nop 0
	s_nop 0
; template <int EPI>
; __device__ void gemm8(const bf16* A, const bf16* Bt, const int K, const int ntN, const int ntTot, const EpiArgs ea, char* smem) {
;     ...
;               for (int j = 0; j < 4; ++j) { float x = acc[ai][bj][m][n][j] * rs; v[bj][n][j] = x; ss += x * x; }
;           float rr = 1.f;
;           if (nsel) {
;             ss += __shfl_xor(ss, 16); ss += __shfl_xor(ss, 32);
;             rr = rsqrtf(ss * (1.f / 64.f) + EPS);
;           }
;           int grow = row;
;           if (dperm) {
;             int b = row >> 13, t = row & (SEQ - 1);
;             grow = b * SEQ + (t & ((1 << sh) - 1)) * (SEQ >> sh) + (t >> sh);
;           }
;           bf16* orow = ea.outb + ((size_t)c * NT + grow) * 64 + fq * 8;
; #pragma unroll
;           for (int bj = 0; bj < 2; ++bj) {
;             u32x4 o;
;             o[0] = pack2(v[bj][0][0] * rr * gv[bj][0][0], v[bj][0][1] * rr * gv[bj][0][1]);
;             o[1] = pack2(v[bj][0][2] * rr * gv[bj][0][2], v[bj][0][3] * rr * gv[bj][0][3]);
;             o[2] = pack2(v[bj][1][0] * rr * gv[bj][1][0], v[bj][1][1] * rr * gv[bj][1][1]);
;             o[3] = pack2(v[bj][1][2] * rr * gv[bj][1][2], v[bj][1][3] * rr * gv[bj][1][3]);
;             *(u32x4*)(orow + bj * 32) = o;
.LBB0_197:
	s_or_b64 exec, exec, s[0:1]
	s_movk_i32 s0, 0x1fef
	v_or_b32_e32 v92, 32, v133
	v_bitop3_b32 v93, v133, s0, 32 bitop3:0xc8
	v_lshlrev_b32_e32 v94, v130, v92
	v_lshrrev_b32_sdwa v93, v164, v93 dst_sel:DWORD dst_unused:UNUSED_PAD src0_sel:WORD_0 src1_sel:DWORD
	v_and_b32_e32 v94, 0x1ffe, v94
	v_or_b32_e32 v93, v93, v132
	v_add_u32_e32 v93, v93, v94
	v_cndmask_b32_e64 v92, v92, v93, s[40:41]
	v_ashrrev_i32_e32 v93, 31, v92
	v_lshlrev_b64 v[92:93], 7, v[92:93]
	v_lshl_add_u64 v[96:97], v[114:115], 0, v[92:93]
	v_mul_f32_e32 v92, v105, v91
	v_mul_f32_e32 v93, v104, v91
	v_mul_f32_e32 v92, v162, v92
	v_mul_f32_e32 v93, v163, v93
	v_cvt_pk_bf16_f32 v92, v92, v93
	v_mul_f32_e32 v93, v103, v91
	v_mul_f32_e32 v94, v102, v91
	v_mul_f32_e32 v93, v144, v93
	v_mul_f32_e32 v94, v145, v94
	v_cvt_pk_bf16_f32 v93, v93, v94
	v_mul_f32_e32 v94, v101, v91
	v_mul_f32_e32 v95, v100, v91
	v_mul_f32_e32 v94, v142, v94
	v_mul_f32_e32 v95, v143, v95
	v_cvt_pk_bf16_f32 v94, v94, v95
	v_mul_f32_e32 v95, v99, v91
	v_mul_f32_e32 v98, v98, v91
	v_mul_f32_e32 v95, v138, v95
	v_mul_f32_e32 v98, v139, v98
	v_cvt_pk_bf16_f32 v95, v95, v98
	ds_read_b32 v98, v161 offset:192
	v_mul_f32_e32 v88, v88, v91
	v_mul_f32_e32 v89, v89, v91
	v_mul_f32_e32 v86, v86, v91
	v_mul_f32_e32 v87, v87, v91
	v_mul_f32_e32 v84, v84, v91
	v_mul_f32_e32 v85, v85, v91
	v_mul_f32_e32 v82, v82, v91
	v_mul_f32_e32 v83, v83, v91
	v_mul_f32_e32 v88, v134, v88
	v_mul_f32_e32 v89, v135, v89
	v_mul_f32_e32 v86, v128, v86
	v_mul_f32_e32 v87, v129, v87
	v_mul_f32_e32 v84, v124, v84
	v_mul_f32_e32 v85, v125, v85
	v_mul_f32_e32 v82, v122, v82
	v_mul_f32_e32 v83, v123, v83
	global_store_dwordx4 v[96:97], v[92:95], off
	s_nop 1
	v_cvt_pk_bf16_f32 v92, v88, v89
	v_cvt_pk_bf16_f32 v93, v86, v87
	v_cvt_pk_bf16_f32 v94, v84, v85
	v_cvt_pk_bf16_f32 v95, v82, v83
	s_waitcnt lgkmcnt(0)
	v_mul_f32_e32 v89, v70, v98
	v_mul_f32_e32 v88, v71, v98
	v_mul_f32_e32 v87, v72, v98
	v_mul_f32_e32 v86, v73, v98
	v_mul_f32_e32 v85, v66, v98
	v_mul_f32_e32 v84, v67, v98
	v_mul_f32_e32 v83, v68, v98
	v_mul_f32_e32 v82, v69, v98
	v_pk_mul_f32 v[72:73], v[78:79], v[98:99] op_sel_hi:[1,0]
	v_pk_mul_f32 v[70:71], v[80:81], v[98:99] op_sel_hi:[1,0]
	v_pk_mul_f32 v[68:69], v[74:75], v[98:99] op_sel_hi:[1,0]
	v_pk_mul_f32 v[66:67], v[76:77], v[98:99] op_sel_hi:[1,0]
	global_store_dwordx4 v[96:97], v[92:95], off offset:64
	s_and_saveexec_b64 s[0:1], s[16:17]
	s_cbranch_execz .LBB0_199
	v_mul_f32_e32 v76, v88, v88
	v_fmac_f32_e32 v76, v89, v89
	v_fmac_f32_e32 v76, v87, v87
	v_fmac_f32_e32 v76, v86, v86
	v_fmac_f32_e32 v76, v85, v85
	v_fmac_f32_e32 v76, v84, v84
	v_fmac_f32_e32 v76, v83, v83
	v_fmac_f32_e32 v76, v82, v82
	v_pk_mul_f32 v[74:75], v[72:73], v[72:73]
	s_nop 0
	v_add_f32_e32 v74, v74, v76
	v_add_f32_e32 v76, v75, v74
	v_pk_mul_f32 v[74:75], v[70:71], v[70:71]
	s_nop 0
	v_add_f32_e32 v74, v74, v76
	v_add_f32_e32 v76, v75, v74
	v_pk_mul_f32 v[74:75], v[68:69], v[68:69]
	s_nop 0
	v_add_f32_e32 v74, v74, v76
	v_add_f32_e32 v76, v75, v74
	v_pk_mul_f32 v[74:75], v[66:67], v[66:67]
	s_nop 0
	v_add_f32_e32 v74, v74, v76
	v_and_b32_e32 v76, 64, v229
	v_add_f32_e32 v74, v75, v74
	v_add_u32_e32 v76, 64, v76
	v_mov_b32_e32 v75, v74
	s_nop 1
	v_permlane16_swap_b32_e32 v75, v74
	s_waitcnt lgkmcnt(0)
	v_add_f32_e32 v74, v74, v75
	v_mov_b32_e32 v75, v74
	s_nop 1
	v_permlane32_swap_b32_e32 v75, v74
	s_waitcnt lgkmcnt(0)
	v_add_f32_e32 v74, v74, v75
	v_fmamk_f32 v74, v74, 0x3c800000, v231
	v_mul_f32_e32 v75, 0x4b800000, v74
	v_cmp_gt_f32_e64 s[4:5], s12, v74
	s_nop 1
	v_cndmask_b32_e64 v74, v74, v75, s[4:5]
	v_rsq_f32_e32 v74, v74
	s_nop 0
	v_mul_f32_e32 v75, 0x45800000, v74
	v_cndmask_b32_e64 v90, v74, v75, s[4:5]
	s_branch .LBB0_199
	s_nop 0
	s_nop 0
	s_nop 0
	s_nop 0
	s_nop 0
	s_nop 0
	s_nop 0
	s_nop 0
	s_nop 0
	s_nop 0
	s_nop 0
.LBB0_199:
	s_or_b64 exec, exec, s[0:1]
	s_movk_i32 s0, 0x1fff
	v_or_b32_e32 v74, 48, v133
	v_bitop3_b32 v75, v133, s0, 48 bitop3:0xc8
	v_lshlrev_b32_e32 v76, v130, v74
	v_lshrrev_b32_sdwa v75, v164, v75 dst_sel:DWORD dst_unused:UNUSED_PAD src0_sel:WORD_0 src1_sel:DWORD
	v_and_b32_e32 v76, 0x1ffe, v76
	v_or_b32_e32 v75, v75, v132
	v_add_u32_e32 v75, v75, v76
	v_cndmask_b32_e64 v74, v74, v75, s[40:41]
	v_ashrrev_i32_e32 v75, 31, v74
	v_lshlrev_b64 v[74:75], 7, v[74:75]
	v_lshl_add_u64 v[78:79], v[114:115], 0, v[74:75]
	v_mul_f32_e32 v74, v89, v90
	v_mul_f32_e32 v75, v88, v90
	v_mul_f32_e32 v74, v162, v74
	v_mul_f32_e32 v75, v163, v75
	v_cvt_pk_bf16_f32 v74, v74, v75
	v_mul_f32_e32 v75, v87, v90
	v_mul_f32_e32 v76, v86, v90
	v_mul_f32_e32 v75, v144, v75
	v_mul_f32_e32 v76, v145, v76
	v_cvt_pk_bf16_f32 v75, v75, v76
	v_mul_f32_e32 v76, v85, v90
	v_mul_f32_e32 v77, v84, v90
	v_mul_f32_e32 v76, v142, v76
	v_mul_f32_e32 v77, v143, v77
	v_cvt_pk_bf16_f32 v76, v76, v77
	v_mul_f32_e32 v77, v83, v90
	v_mul_f32_e32 v80, v82, v90
	v_mul_f32_e32 v77, v138, v77
	v_mul_f32_e32 v80, v139, v80
	v_cvt_pk_bf16_f32 v77, v77, v80
	global_store_dwordx4 v[78:79], v[74:77], off
	ds_read_b32 v76, v161 offset:512
	v_mul_f32_e32 v72, v72, v90
	v_mul_f32_e32 v73, v73, v90
	v_mul_f32_e32 v70, v70, v90
	v_mul_f32_e32 v71, v71, v90
	v_mul_f32_e32 v68, v68, v90
	v_mul_f32_e32 v69, v69, v90
	v_mul_f32_e32 v66, v66, v90
	v_mul_f32_e32 v67, v67, v90
	v_mul_f32_e32 v72, v134, v72
	v_mul_f32_e32 v73, v135, v73
	v_mul_f32_e32 v70, v128, v70
	v_mul_f32_e32 v71, v129, v71
	v_mul_f32_e32 v68, v124, v68
	v_mul_f32_e32 v69, v125, v69
	v_mul_f32_e32 v66, v122, v66
	v_mul_f32_e32 v67, v123, v67
	v_cvt_pk_bf16_f32 v72, v72, v73
	v_cvt_pk_bf16_f32 v73, v70, v71
	v_cvt_pk_bf16_f32 v74, v68, v69
	v_cvt_pk_bf16_f32 v75, v66, v67
	global_store_dwordx4 v[78:79], v[72:75], off offset:64
	s_waitcnt lgkmcnt(0)
	v_mul_f32_e32 v71, v56, v76
	v_mul_f32_e32 v70, v57, v76
	v_mul_f32_e32 v73, v54, v76
	v_mul_f32_e32 v72, v55, v76
	v_mul_f32_e32 v69, v50, v76
	v_mul_f32_e32 v68, v51, v76
	v_mul_f32_e32 v67, v52, v76
	v_mul_f32_e32 v66, v53, v76
	v_pk_mul_f32 v[56:57], v[62:63], v[76:77] op_sel_hi:[1,0]
	v_pk_mul_f32 v[54:55], v[64:65], v[76:77] op_sel_hi:[1,0]
	v_pk_mul_f32 v[52:53], v[58:59], v[76:77] op_sel_hi:[1,0]
	v_pk_mul_f32 v[50:51], v[60:61], v[76:77] op_sel_hi:[1,0]
	v_mov_b32_e32 v60, 1.0
	v_mov_b32_e32 v61, 1.0
	s_and_saveexec_b64 s[0:1], s[16:17]
	s_cbranch_execz .LBB0_201
; template <int EPI>
; __device__ void gemm8(const bf16* A, const bf16* Bt, const int K, const int ntN, const int ntTot, const EpiArgs ea, char* smem) {
;     ...
;               for (int j = 0; j < 4; ++j) { float x = acc[ai][bj][m][n][j] * rs; v[bj][n][j] = x; ss += x * x; }
;           float rr = 1.f;
;           if (nsel) {
;             ss += __shfl_xor(ss, 16); ss += __shfl_xor(ss, 32);
;             rr = rsqrtf(ss * (1.f / 64.f) + EPS);
;           }
;           int grow = row;
;           if (dperm) {
;             int b = row >> 13, t = row & (SEQ - 1);
;             grow = b * SEQ + (t & ((1 << sh) - 1)) * (SEQ >> sh) + (t >> sh);
;           }
;           bf16* orow = ea.outb + ((size_t)c * NT + grow) * 64 + fq * 8;
; #pragma unroll
;           for (int bj = 0; bj < 2; ++bj) {
;             u32x4 o;
;             o[0] = pack2(v[bj][0][0] * rr * gv[bj][0][0], v[bj][0][1] * rr * gv[bj][0][1]);
;             o[1] = pack2(v[bj][0][2] * rr * gv[bj][0][2], v[bj][0][3] * rr * gv[bj][0][3]);
;             o[2] = pack2(v[bj][1][0] * rr * gv[bj][1][0], v[bj][1][1] * rr * gv[bj][1][1]);
;             o[3] = pack2(v[bj][1][2] * rr * gv[bj][1][2], v[bj][1][3] * rr * gv[bj][1][3]);
;             *(u32x4*)(orow + bj * 32) = o;
	v_mul_f32_e32 v61, v72, v72
	v_fmac_f32_e32 v61, v73, v73
	v_fmac_f32_e32 v61, v71, v71
	v_fmac_f32_e32 v61, v70, v70
	v_fmac_f32_e32 v61, v69, v69
	v_fmac_f32_e32 v61, v68, v68
	v_fmac_f32_e32 v61, v67, v67
	v_fmac_f32_e32 v61, v66, v66
	v_pk_mul_f32 v[58:59], v[56:57], v[56:57]
	s_nop 0
	v_add_f32_e32 v58, v58, v61
	v_add_f32_e32 v61, v59, v58
	v_pk_mul_f32 v[58:59], v[54:55], v[54:55]
	s_nop 0
	v_add_f32_e32 v58, v58, v61
	v_add_f32_e32 v61, v59, v58
	v_pk_mul_f32 v[58:59], v[52:53], v[52:53]
	s_nop 0
	v_add_f32_e32 v58, v58, v61
	v_add_f32_e32 v61, v59, v58
	v_pk_mul_f32 v[58:59], v[50:51], v[50:51]
	s_nop 0
	v_add_f32_e32 v58, v58, v61
	v_and_b32_e32 v61, 64, v229
	v_add_f32_e32 v58, v59, v58
	v_add_u32_e32 v61, 64, v61
	v_mov_b32_e32 v59, v58
	s_nop 1
	v_permlane16_swap_b32_e32 v59, v58
	s_waitcnt lgkmcnt(0)
	v_add_f32_e32 v58, v58, v59
	v_mov_b32_e32 v59, v58
	s_nop 1
	v_permlane32_swap_b32_e32 v59, v58
	s_waitcnt lgkmcnt(0)
	v_add_f32_e32 v58, v58, v59
	v_fmamk_f32 v58, v58, 0x3c800000, v231
	v_mul_f32_e32 v59, 0x4b800000, v58
	v_cmp_gt_f32_e64 s[4:5], s12, v58
	s_nop 1
	v_cndmask_b32_e64 v58, v58, v59, s[4:5]
	v_rsq_f32_e32 v58, v58
	s_nop 0
	v_mul_f32_e32 v59, 0x45800000, v58
	v_cndmask_b32_e64 v61, v58, v59, s[4:5]
	s_branch .LBB0_201
	s_nop 0
	s_nop 0
	s_nop 0
	s_nop 0
	s_nop 0
	s_nop 0
	s_nop 0
	s_nop 0
	s_nop 0
	s_nop 0
	s_nop 0
.LBB0_201:
	s_or_b64 exec, exec, s[0:1]
	v_add_u32_e32 v62, 0x80, v131
	v_or_b32_e32 v59, v62, v156
	v_and_b32_e32 v58, 0xffffe000, v62
	v_bitop3_b32 v62, v62, s28, v156 bitop3:0xc8
	v_lshlrev_b32_e32 v63, v130, v59
	v_lshrrev_b32_sdwa v62, v164, v62 dst_sel:DWORD dst_unused:UNUSED_PAD src0_sel:WORD_0 src1_sel:DWORD
	v_and_b32_e32 v63, 0x1ffe, v63
	v_or_b32_e32 v62, v62, v58
	v_add_u32_e32 v62, v62, v63
	v_cndmask_b32_e64 v62, v59, v62, s[40:41]
	v_ashrrev_i32_e32 v63, 31, v62
	v_lshlrev_b64 v[62:63], 7, v[62:63]
	v_lshl_add_u64 v[74:75], v[114:115], 0, v[62:63]
	v_mul_f32_e32 v62, v73, v61
	v_mul_f32_e32 v63, v72, v61
	v_mul_f32_e32 v62, v162, v62
	v_mul_f32_e32 v63, v163, v63
	v_cvt_pk_bf16_f32 v62, v62, v63
	v_mul_f32_e32 v63, v71, v61
	v_mul_f32_e32 v64, v70, v61
	v_mul_f32_e32 v63, v144, v63
	v_mul_f32_e32 v64, v145, v64
	v_cvt_pk_bf16_f32 v63, v63, v64
	v_mul_f32_e32 v64, v69, v61
	v_mul_f32_e32 v65, v68, v61
	v_mul_f32_e32 v64, v142, v64
	v_mul_f32_e32 v65, v143, v65
	v_cvt_pk_bf16_f32 v64, v64, v65
	v_mul_f32_e32 v65, v67, v61
	v_mul_f32_e32 v66, v66, v61
	v_mul_f32_e32 v65, v138, v65
	v_mul_f32_e32 v66, v139, v66
	v_cvt_pk_bf16_f32 v65, v65, v66
	ds_read_b32 v66, v161 offset:576
	v_mul_f32_e32 v56, v56, v61
	v_mul_f32_e32 v57, v57, v61
	v_mul_f32_e32 v54, v54, v61
	v_mul_f32_e32 v55, v55, v61
	v_mul_f32_e32 v52, v52, v61
	v_mul_f32_e32 v53, v53, v61
	v_mul_f32_e32 v50, v50, v61
	v_mul_f32_e32 v51, v51, v61
	v_mul_f32_e32 v56, v134, v56
	v_mul_f32_e32 v57, v135, v57
	v_mul_f32_e32 v54, v128, v54
	v_mul_f32_e32 v55, v129, v55
	v_mul_f32_e32 v52, v124, v52
	v_mul_f32_e32 v53, v125, v53
	v_mul_f32_e32 v50, v122, v50
	v_mul_f32_e32 v51, v123, v51
	global_store_dwordx4 v[74:75], v[62:65], off
	s_nop 1
	v_cvt_pk_bf16_f32 v62, v56, v57
	v_cvt_pk_bf16_f32 v63, v54, v55
	v_cvt_pk_bf16_f32 v64, v52, v53
	v_cvt_pk_bf16_f32 v65, v50, v51
	s_waitcnt lgkmcnt(0)
	v_mul_f32_e32 v57, v38, v66
	v_mul_f32_e32 v56, v39, v66
	v_mul_f32_e32 v55, v40, v66
	v_mul_f32_e32 v54, v41, v66
	v_mul_f32_e32 v53, v34, v66
	v_mul_f32_e32 v52, v35, v66
	v_mul_f32_e32 v51, v36, v66
	v_mul_f32_e32 v50, v37, v66
	v_pk_mul_f32 v[40:41], v[46:47], v[66:67] op_sel_hi:[1,0]
	v_pk_mul_f32 v[38:39], v[48:49], v[66:67] op_sel_hi:[1,0]
	v_pk_mul_f32 v[36:37], v[42:43], v[66:67] op_sel_hi:[1,0]
	v_pk_mul_f32 v[34:35], v[44:45], v[66:67] op_sel_hi:[1,0]
	global_store_dwordx4 v[74:75], v[62:65], off offset:64
	s_and_saveexec_b64 s[0:1], s[16:17]
	s_cbranch_execz .LBB0_203
	v_mul_f32_e32 v44, v56, v56
	v_fmac_f32_e32 v44, v57, v57
	v_fmac_f32_e32 v44, v55, v55
	v_fmac_f32_e32 v44, v54, v54
	v_fmac_f32_e32 v44, v53, v53
	v_fmac_f32_e32 v44, v52, v52
	v_fmac_f32_e32 v44, v51, v51
	v_fmac_f32_e32 v44, v50, v50
	v_pk_mul_f32 v[42:43], v[40:41], v[40:41]
	s_nop 0
	v_add_f32_e32 v42, v42, v44
	v_add_f32_e32 v44, v43, v42
	v_pk_mul_f32 v[42:43], v[38:39], v[38:39]
	s_nop 0
	v_add_f32_e32 v42, v42, v44
	v_add_f32_e32 v44, v43, v42
	v_pk_mul_f32 v[42:43], v[36:37], v[36:37]
	s_nop 0
	v_add_f32_e32 v42, v42, v44
	v_add_f32_e32 v44, v43, v42
	v_pk_mul_f32 v[42:43], v[34:35], v[34:35]
	s_nop 0
	v_add_f32_e32 v42, v42, v44
	v_and_b32_e32 v44, 64, v229
	v_add_f32_e32 v42, v43, v42
	v_add_u32_e32 v44, 64, v44
	v_mov_b32_e32 v43, v42
	s_nop 1
	v_permlane16_swap_b32_e32 v43, v42
	s_waitcnt lgkmcnt(0)
	v_add_f32_e32 v42, v42, v43
	v_mov_b32_e32 v43, v42
	s_nop 1
	v_permlane32_swap_b32_e32 v43, v42
	s_waitcnt lgkmcnt(0)
	v_add_f32_e32 v42, v42, v43
	v_fmamk_f32 v42, v42, 0x3c800000, v231
	v_mul_f32_e32 v43, 0x4b800000, v42
	v_cmp_gt_f32_e64 s[4:5], s12, v42
	s_nop 1
	v_cndmask_b32_e64 v42, v42, v43, s[4:5]
	v_rsq_f32_e32 v42, v42
	s_nop 0
	v_mul_f32_e32 v43, 0x45800000, v42
	v_cndmask_b32_e64 v60, v42, v43, s[4:5]
	s_branch .LBB0_203
	s_nop 0
	s_nop 0
	s_nop 0
	s_nop 0
	s_nop 0
	s_nop 0
	s_nop 0
	s_nop 0
	s_nop 0
	s_nop 0
	s_nop 0
; template <int EPI>
; __device__ void gemm8(const bf16* A, const bf16* Bt, const int K, const int ntN, const int ntTot, const EpiArgs ea, char* smem) {
;     ...
;               for (int j = 0; j < 4; ++j) { float x = acc[ai][bj][m][n][j] * rs; v[bj][n][j] = x; ss += x * x; }
;           float rr = 1.f;
;           if (nsel) {
;             ss += __shfl_xor(ss, 16); ss += __shfl_xor(ss, 32);
;             rr = rsqrtf(ss * (1.f / 64.f) + EPS);
;           }
;           int grow = row;
;           if (dperm) {
;             int b = row >> 13, t = row & (SEQ - 1);
;             grow = b * SEQ + (t & ((1 << sh) - 1)) * (SEQ >> sh) + (t >> sh);
;           }
;           bf16* orow = ea.outb + ((size_t)c * NT + grow) * 64 + fq * 8;
; #pragma unroll
;           for (int bj = 0; bj < 2; ++bj) {
;             u32x4 o;
;             o[0] = pack2(v[bj][0][0] * rr * gv[bj][0][0], v[bj][0][1] * rr * gv[bj][0][1]);
;             o[1] = pack2(v[bj][0][2] * rr * gv[bj][0][2], v[bj][0][3] * rr * gv[bj][0][3]);
;             o[2] = pack2(v[bj][1][0] * rr * gv[bj][1][0], v[bj][1][1] * rr * gv[bj][1][1]);
;             o[3] = pack2(v[bj][1][2] * rr * gv[bj][1][2], v[bj][1][3] * rr * gv[bj][1][3]);
;             *(u32x4*)(orow + bj * 32) = o;
.LBB0_203:
	s_or_b64 exec, exec, s[0:1]
	v_or_b32_e32 v42, 16, v59
	v_bitop3_b32 v43, v59, s29, 16 bitop3:0xc8
	v_lshlrev_b32_e32 v44, v130, v42
	v_lshrrev_b32_sdwa v43, v164, v43 dst_sel:DWORD dst_unused:UNUSED_PAD src0_sel:WORD_0 src1_sel:DWORD
	v_and_b32_e32 v44, 0x1ffe, v44
	v_or_b32_e32 v43, v43, v58
	v_add_u32_e32 v43, v43, v44
	v_cndmask_b32_e64 v42, v42, v43, s[40:41]
	v_ashrrev_i32_e32 v43, 31, v42
	v_lshlrev_b64 v[42:43], 7, v[42:43]
	v_lshl_add_u64 v[46:47], v[114:115], 0, v[42:43]
	v_mul_f32_e32 v42, v57, v60
	v_mul_f32_e32 v43, v56, v60
	v_mul_f32_e32 v42, v162, v42
	v_mul_f32_e32 v43, v163, v43
	v_cvt_pk_bf16_f32 v42, v42, v43
	v_mul_f32_e32 v43, v55, v60
	v_mul_f32_e32 v44, v54, v60
	v_mul_f32_e32 v43, v144, v43
	v_mul_f32_e32 v44, v145, v44
	v_cvt_pk_bf16_f32 v43, v43, v44
	v_mul_f32_e32 v44, v53, v60
	v_mul_f32_e32 v45, v52, v60
	v_mul_f32_e32 v44, v142, v44
	v_mul_f32_e32 v45, v143, v45
	v_cvt_pk_bf16_f32 v44, v44, v45
	v_mul_f32_e32 v45, v51, v60
	v_mul_f32_e32 v48, v50, v60
	v_mul_f32_e32 v45, v138, v45
	v_mul_f32_e32 v48, v139, v48
	v_cvt_pk_bf16_f32 v45, v45, v48
	global_store_dwordx4 v[46:47], v[42:45], off
	ds_read_b32 v44, v161 offset:640
	v_mul_f32_e32 v40, v40, v60
	v_mul_f32_e32 v41, v41, v60
	v_mul_f32_e32 v38, v38, v60
	v_mul_f32_e32 v39, v39, v60
	v_mul_f32_e32 v36, v36, v60
	v_mul_f32_e32 v37, v37, v60
	v_mul_f32_e32 v34, v34, v60
	v_mul_f32_e32 v35, v35, v60
	v_mul_f32_e32 v40, v134, v40
	v_mul_f32_e32 v41, v135, v41
	v_mul_f32_e32 v38, v128, v38
	v_mul_f32_e32 v39, v129, v39
	v_mul_f32_e32 v36, v124, v36
	v_mul_f32_e32 v37, v125, v37
	v_mul_f32_e32 v34, v122, v34
	v_mul_f32_e32 v35, v123, v35
	v_cvt_pk_bf16_f32 v40, v40, v41
	v_cvt_pk_bf16_f32 v41, v38, v39
	v_cvt_pk_bf16_f32 v42, v36, v37
	v_cvt_pk_bf16_f32 v43, v34, v35
	global_store_dwordx4 v[46:47], v[40:43], off offset:64
	s_waitcnt lgkmcnt(0)
	v_mul_f32_e32 v39, v24, v44
	v_mul_f32_e32 v38, v25, v44
	v_mul_f32_e32 v41, v22, v44
	v_mul_f32_e32 v40, v23, v44
	v_mul_f32_e32 v37, v18, v44
	v_mul_f32_e32 v36, v19, v44
	v_mul_f32_e32 v35, v20, v44
	v_mul_f32_e32 v34, v21, v44
	v_pk_mul_f32 v[24:25], v[30:31], v[44:45] op_sel_hi:[1,0]
	v_pk_mul_f32 v[22:23], v[32:33], v[44:45] op_sel_hi:[1,0]
	v_pk_mul_f32 v[20:21], v[26:27], v[44:45] op_sel_hi:[1,0]
	v_pk_mul_f32 v[18:19], v[28:29], v[44:45] op_sel_hi:[1,0]
	v_mov_b32_e32 v26, 1.0
	v_mov_b32_e32 v27, 1.0
	s_and_saveexec_b64 s[0:1], s[16:17]
	s_cbranch_execz .LBB0_205
	v_mul_f32_e32 v27, v40, v40
	v_fmac_f32_e32 v27, v41, v41
	v_fmac_f32_e32 v27, v39, v39
	v_fmac_f32_e32 v27, v38, v38
	v_fmac_f32_e32 v27, v37, v37
	v_fmac_f32_e32 v27, v36, v36
	v_fmac_f32_e32 v27, v35, v35
	v_fmac_f32_e32 v27, v34, v34
	v_pk_mul_f32 v[28:29], v[24:25], v[24:25]
	s_nop 0
	v_add_f32_e32 v27, v28, v27
	v_add_f32_e32 v27, v29, v27
	v_pk_mul_f32 v[28:29], v[22:23], v[22:23]
	s_nop 0
	v_add_f32_e32 v27, v28, v27
	v_add_f32_e32 v27, v29, v27
	v_pk_mul_f32 v[28:29], v[20:21], v[20:21]
	s_nop 0
	v_add_f32_e32 v27, v28, v27
	v_add_f32_e32 v27, v29, v27
	v_pk_mul_f32 v[28:29], v[18:19], v[18:19]
	s_nop 0
	v_add_f32_e32 v27, v28, v27
	v_add_f32_e32 v27, v29, v27
	v_and_b32_e32 v29, 64, v229
	v_add_u32_e32 v29, 64, v29
	v_mov_b32_e32 v28, v27
	s_nop 1
	v_permlane16_swap_b32_e32 v28, v27
	s_waitcnt lgkmcnt(0)
	v_add_f32_e32 v27, v27, v28
	v_mov_b32_e32 v28, v27
	s_nop 1
	v_permlane32_swap_b32_e32 v28, v27
	s_waitcnt lgkmcnt(0)
	v_add_f32_e32 v27, v27, v28
	v_fmamk_f32 v27, v27, 0x3c800000, v231
	v_mul_f32_e32 v28, 0x4b800000, v27
	v_cmp_gt_f32_e64 s[4:5], s12, v27
	s_nop 1
	v_cndmask_b32_e64 v27, v27, v28, s[4:5]
	v_rsq_f32_e32 v27, v27
	s_nop 0
	v_mul_f32_e32 v28, 0x45800000, v27
	v_cndmask_b32_e64 v27, v27, v28, s[4:5]
	s_branch .LBB0_205
	s_nop 0
	s_nop 0
	s_nop 0
	s_nop 0
	s_nop 0
	s_nop 0
	s_nop 0
	s_nop 0
	s_nop 0
	s_nop 0
	s_nop 0
; template <int EPI>
; __device__ void gemm8(const bf16* A, const bf16* Bt, const int K, const int ntN, const int ntTot, const EpiArgs ea, char* smem) {
;     ...
;               for (int j = 0; j < 4; ++j) { float x = acc[ai][bj][m][n][j] * rs; v[bj][n][j] = x; ss += x * x; }
;           float rr = 1.f;
;           if (nsel) {
;             ss += __shfl_xor(ss, 16); ss += __shfl_xor(ss, 32);
;             rr = rsqrtf(ss * (1.f / 64.f) + EPS);
;           }
;           int grow = row;
;           if (dperm) {
;             int b = row >> 13, t = row & (SEQ - 1);
;             grow = b * SEQ + (t & ((1 << sh) - 1)) * (SEQ >> sh) + (t >> sh);
;           }
;           bf16* orow = ea.outb + ((size_t)c * NT + grow) * 64 + fq * 8;
; #pragma unroll
;           for (int bj = 0; bj < 2; ++bj) {
;             u32x4 o;
;             o[0] = pack2(v[bj][0][0] * rr * gv[bj][0][0], v[bj][0][1] * rr * gv[bj][0][1]);
;             o[1] = pack2(v[bj][0][2] * rr * gv[bj][0][2], v[bj][0][3] * rr * gv[bj][0][3]);
;             o[2] = pack2(v[bj][1][0] * rr * gv[bj][1][0], v[bj][1][1] * rr * gv[bj][1][1]);
;             o[3] = pack2(v[bj][1][2] * rr * gv[bj][1][2], v[bj][1][3] * rr * gv[bj][1][3]);
;             *(u32x4*)(orow + bj * 32) = o;
.LBB0_205:
	s_or_b64 exec, exec, s[0:1]
	s_movk_i32 s0, 0x1fef
	v_or_b32_e32 v28, 32, v59
	v_bitop3_b32 v29, v59, s0, 32 bitop3:0xc8
	v_lshlrev_b32_e32 v30, v130, v28
	v_lshrrev_b32_sdwa v29, v164, v29 dst_sel:DWORD dst_unused:UNUSED_PAD src0_sel:WORD_0 src1_sel:DWORD
	v_and_b32_e32 v30, 0x1ffe, v30
	v_or_b32_e32 v29, v29, v58
	v_add_u32_e32 v29, v29, v30
	v_cndmask_b32_e64 v28, v28, v29, s[40:41]
	v_ashrrev_i32_e32 v29, 31, v28
	v_lshlrev_b64 v[28:29], 7, v[28:29]
	v_lshl_add_u64 v[32:33], v[114:115], 0, v[28:29]
	v_mul_f32_e32 v28, v41, v27
	v_mul_f32_e32 v29, v40, v27
	v_mul_f32_e32 v28, v162, v28
	v_mul_f32_e32 v29, v163, v29
	v_cvt_pk_bf16_f32 v28, v28, v29
	v_mul_f32_e32 v29, v39, v27
	v_mul_f32_e32 v30, v38, v27
	v_mul_f32_e32 v29, v144, v29
	v_mul_f32_e32 v30, v145, v30
	v_cvt_pk_bf16_f32 v29, v29, v30
	v_mul_f32_e32 v30, v37, v27
	v_mul_f32_e32 v31, v36, v27
	v_mul_f32_e32 v30, v142, v30
	v_mul_f32_e32 v31, v143, v31
	v_cvt_pk_bf16_f32 v30, v30, v31
	v_mul_f32_e32 v31, v35, v27
	v_mul_f32_e32 v34, v34, v27
	v_mul_f32_e32 v31, v138, v31
	v_mul_f32_e32 v34, v139, v34
	v_cvt_pk_bf16_f32 v31, v31, v34
	ds_read_b32 v34, v161 offset:704
	v_mul_f32_e32 v24, v24, v27
	v_mul_f32_e32 v25, v25, v27
	v_mul_f32_e32 v22, v22, v27
	v_mul_f32_e32 v23, v23, v27
	v_mul_f32_e32 v20, v20, v27
	v_mul_f32_e32 v21, v21, v27
	v_mul_f32_e32 v18, v18, v27
	v_mul_f32_e32 v19, v19, v27
	v_mul_f32_e32 v24, v134, v24
	v_mul_f32_e32 v25, v135, v25
	v_mul_f32_e32 v22, v128, v22
	v_mul_f32_e32 v23, v129, v23
	v_mul_f32_e32 v20, v124, v20
	v_mul_f32_e32 v21, v125, v21
	v_mul_f32_e32 v18, v122, v18
	v_mul_f32_e32 v19, v123, v19
	global_store_dwordx4 v[32:33], v[28:31], off
	s_nop 1
	v_cvt_pk_bf16_f32 v28, v24, v25
	v_cvt_pk_bf16_f32 v29, v22, v23
	v_cvt_pk_bf16_f32 v30, v20, v21
	v_cvt_pk_bf16_f32 v31, v18, v19
	s_waitcnt lgkmcnt(0)
	v_mul_f32_e32 v25, v6, v34
	v_mul_f32_e32 v24, v7, v34
	v_mul_f32_e32 v23, v8, v34
	v_mul_f32_e32 v22, v9, v34
	v_mul_f32_e32 v21, v2, v34
	v_mul_f32_e32 v20, v3, v34
	v_mul_f32_e32 v19, v4, v34
	v_mul_f32_e32 v18, v5, v34
	v_pk_mul_f32 v[8:9], v[14:15], v[34:35] op_sel_hi:[1,0]
	v_pk_mul_f32 v[6:7], v[16:17], v[34:35] op_sel_hi:[1,0]
	v_pk_mul_f32 v[4:5], v[10:11], v[34:35] op_sel_hi:[1,0]
	v_pk_mul_f32 v[2:3], v[12:13], v[34:35] op_sel_hi:[1,0]
	global_store_dwordx4 v[32:33], v[28:31], off offset:64
	s_and_saveexec_b64 s[0:1], s[16:17]
	s_cbranch_execz .LBB0_170
	v_mul_f32_e32 v12, v24, v24
	v_fmac_f32_e32 v12, v25, v25
	v_fmac_f32_e32 v12, v23, v23
	v_fmac_f32_e32 v12, v22, v22
	v_fmac_f32_e32 v12, v21, v21
	v_fmac_f32_e32 v12, v20, v20
	v_fmac_f32_e32 v12, v19, v19
	v_fmac_f32_e32 v12, v18, v18
	v_pk_mul_f32 v[10:11], v[8:9], v[8:9]
	s_nop 0
	v_add_f32_e32 v10, v10, v12
	v_add_f32_e32 v12, v11, v10
	v_pk_mul_f32 v[10:11], v[6:7], v[6:7]
	s_nop 0
	v_add_f32_e32 v10, v10, v12
	v_add_f32_e32 v12, v11, v10
	v_pk_mul_f32 v[10:11], v[4:5], v[4:5]
	s_nop 0
	v_add_f32_e32 v10, v10, v12
	v_add_f32_e32 v12, v11, v10
	v_pk_mul_f32 v[10:11], v[2:3], v[2:3]
	s_nop 0
	v_add_f32_e32 v10, v10, v12
	v_and_b32_e32 v12, 64, v229
	v_add_f32_e32 v10, v11, v10
	v_add_u32_e32 v12, 64, v12
	v_mov_b32_e32 v11, v10
	s_nop 1
	v_permlane16_swap_b32_e32 v11, v10
	s_waitcnt lgkmcnt(0)
	v_add_f32_e32 v10, v10, v11
	v_mov_b32_e32 v11, v10
	s_nop 1
	v_permlane32_swap_b32_e32 v11, v10
	s_waitcnt lgkmcnt(0)
	v_add_f32_e32 v10, v10, v11
	v_fmamk_f32 v10, v10, 0x3c800000, v231
	v_mul_f32_e32 v11, 0x4b800000, v10
	v_cmp_gt_f32_e64 s[4:5], s12, v10
	s_nop 1
	v_cndmask_b32_e64 v10, v10, v11, s[4:5]
	v_rsq_f32_e32 v10, v10
	s_nop 0
	v_mul_f32_e32 v11, 0x45800000, v10
	v_cndmask_b32_e64 v26, v10, v11, s[4:5]
	s_branch .LBB0_170
	s_branch .LBB0_207
	s_nop 0
	s_nop 0
	s_nop 0
	s_nop 0
	s_nop 0
	s_nop 0
	s_nop 0
	s_nop 0
	s_nop 0
	s_nop 0
	s_nop 0

; DI float fexp2(float x) { return __builtin_amdgcn_exp2f(x); }
; DI void softmax_step(int tid, int cls, f32x16 (&S)[2], f32x16 (&O)[2], float& m, float& l, int k0, int qpos, float slope2,
;                      int kmul, int kadd, int W, bool extra) {
;     ...
;     mx += b0;
;     mx = fmaxf(mx, __shfl_xor(mx, 32));
;     if (__any(mx > m + 8.f)) {
;       float mn = fmaxf(m, mx), alpha = fexp2(m - mn);
;       m = mn; l *= alpha;
; #pragma unroll
;       for (int dt = 0; dt < 2; ++dt)
; #pragma unroll
;         for (int i = 0; i < 16; ++i) O[dt][i] *= alpha;
;     }
.LBB0_307:
	s_or_b64 exec, exec, s[0:1]
	s_nop 0
	v_cvt_f32_i32_e32 v48, v126
	v_and_b32_e32 v50, 64, v229
	v_xor_b32_e32 v49, 32, v229
	v_add_u32_e32 v50, 64, v50
	v_cmp_lt_i32_e32 vcc, v49, v50
	v_fma_f32 v51, -v98, v48, v127
	v_add_f32_e32 v50, 0x41000000, v119
	v_cndmask_b32_e32 v49, v229, v49, vcc
	v_lshlrev_b32_e32 v49, 2, v49
	v_mov_b32_e32 v49, v51
	s_nop 1
	v_permlane32_swap_b32_e32 v49, v51
	s_waitcnt lgkmcnt(0)
	v_max_f32_e32 v49, v51, v49
	v_cmp_gt_f32_e32 vcc, v49, v50
	s_cbranch_vccz .LBB0_309
	v_max_f32_e32 v49, v49, v49
	v_max_f32_e32 v50, v119, v119
	v_max_f32_e32 v49, v50, v49
	v_sub_f32_e32 v50, v119, v49
	v_exp_f32_e32 v50, v50
	v_mov_b32_e32 v119, v49
	v_mul_f32_e32 v120, v120, v50
	v_pk_mul_f32 v[30:31], v[30:31], v[50:51] op_sel_hi:[1,0]
	v_pk_mul_f32 v[28:29], v[28:29], v[50:51] op_sel_hi:[1,0]
	v_pk_mul_f32 v[26:27], v[26:27], v[50:51] op_sel_hi:[1,0]
	v_pk_mul_f32 v[24:25], v[24:25], v[50:51] op_sel_hi:[1,0]
	v_pk_mul_f32 v[22:23], v[22:23], v[50:51] op_sel_hi:[1,0]
	v_pk_mul_f32 v[20:21], v[20:21], v[50:51] op_sel_hi:[1,0]
	v_pk_mul_f32 v[18:19], v[18:19], v[50:51] op_sel_hi:[1,0]
	v_pk_mul_f32 v[16:17], v[16:17], v[50:51] op_sel_hi:[1,0]
	v_pk_mul_f32 v[46:47], v[46:47], v[50:51] op_sel_hi:[1,0]
	v_pk_mul_f32 v[44:45], v[44:45], v[50:51] op_sel_hi:[1,0]
	v_pk_mul_f32 v[42:43], v[42:43], v[50:51] op_sel_hi:[1,0]
	v_pk_mul_f32 v[40:41], v[40:41], v[50:51] op_sel_hi:[1,0]
	v_pk_mul_f32 v[38:39], v[38:39], v[50:51] op_sel_hi:[1,0]
	v_pk_mul_f32 v[36:37], v[36:37], v[50:51] op_sel_hi:[1,0]
	v_pk_mul_f32 v[34:35], v[34:35], v[50:51] op_sel_hi:[1,0]
	v_pk_mul_f32 v[32:33], v[32:33], v[50:51] op_sel_hi:[1,0]

; DI void softmax_step(int tid, int cls, f32x16 (&S)[2], f32x16 (&O)[2], float& m, float& l, int k0, int qpos, float slope2,
;                      int kmul, int kadd, int W, bool extra) {
;     ...
;   } else {
; #pragma unroll
;     for (int kt = 0; kt < 2; ++kt)
; #pragma unroll
;       for (int i = 0; i < 16; ++i) {
;         int d = dbase - (kt * 32 + (i & 3) + 8 * (i >> 2)) * kmul;
;         bool valid = extra && ((unsigned)d <= (unsigned)W);
;         float s2 = valid ? fmaf(-slope2, (float)d, S[kt][i]) : NEGB;
;         S[kt][i] = s2;
;         mx = fmaxf(mx, s2);
;       }
;     mx = fmaxf(mx, __shfl_xor(mx, 32));
;     if (__any(mx > m + 8.f)) {
.LBB0_310:
	s_andn2_saveexec_b64 s[0:1], s[16:17]
	s_cbranch_execz .LBB0_289
	v_subrev_u32_e32 v0, 32, v128
	v_cvt_f32_i32_e32 v2, v126
	v_cvt_f32_i32_e32 v3, v0
	v_add_u32_e32 v6, -3, v126
	v_add_u32_e32 v7, -2, v126
	s_movk_i32 s2, 0x81
	v_cvt_f32_i32_e32 v5, v6
	v_cvt_f32_i32_e32 v4, v7
	v_pk_fma_f32 v[2:3], v[100:101], v[2:3], v[64:65]
	v_cmp_gt_u32_e32 vcc, s2, v0
	v_add_u32_e32 v9, -8, v126
	s_mov_b32 s3, 0xf149f2ca
	v_cndmask_b32_e32 v125, v230, v3, vcc
	v_cmp_gt_u32_e32 vcc, s2, v126
	v_add_u32_e32 v10, -11, v126
	v_add_u32_e32 v11, -10, v126
	v_cndmask_b32_e32 v0, v230, v2, vcc
	v_cmp_gt_u32_e32 vcc, s2, v6
	v_add_u32_e32 v6, -9, v126
	v_pk_fma_f32 v[2:3], v[100:101], v[4:5], v[66:67]
	v_cvt_f32_i32_e32 v5, v6
	v_cvt_f32_i32_e32 v4, v9
	v_cndmask_b32_e32 v3, v230, v3, vcc
	v_cmp_gt_u32_e32 vcc, s2, v7
	v_max3_f32 v8, v0, s3, v125
	v_pk_fma_f32 v[4:5], v[100:101], v[4:5], v[68:69]
	v_cndmask_b32_e32 v2, v230, v2, vcc
	v_cmp_gt_u32_e32 vcc, s2, v6
	v_cvt_f32_i32_e32 v7, v10
	v_cvt_f32_i32_e32 v6, v11
	v_cndmask_b32_e32 v5, v230, v5, vcc
	v_cmp_gt_u32_e32 vcc, s2, v9
	v_max3_f32 v8, v8, v2, v3
	v_add_u32_e32 v13, -16, v126
	v_cndmask_b32_e32 v4, v230, v4, vcc
	v_cmp_gt_u32_e32 vcc, s2, v10
	v_subrev_u32_e32 v10, 17, v126
	v_max3_f32 v12, v8, v4, v5
	v_cvt_f32_i32_e32 v8, v13
	v_cvt_f32_i32_e32 v9, v10
	v_pk_fma_f32 v[6:7], v[100:101], v[6:7], v[70:71]
	v_subrev_u32_e32 v14, 19, v126
	v_cndmask_b32_e32 v7, v230, v7, vcc
	v_cmp_gt_u32_e32 vcc, s2, v11
	v_subrev_u32_e32 v15, 18, v126
	v_pk_fma_f32 v[8:9], v[100:101], v[8:9], v[72:73]
	v_cndmask_b32_e32 v6, v230, v6, vcc
	v_cmp_gt_u32_e32 vcc, s2, v10
	v_cvt_f32_i32_e32 v11, v14
	v_cvt_f32_i32_e32 v10, v15
	v_cndmask_b32_e32 v9, v230, v9, vcc
	v_cmp_gt_u32_e32 vcc, s2, v13
	v_max3_f32 v12, v12, v6, v7
	v_subrev_u32_e32 v65, 24, v126
	v_cndmask_b32_e32 v8, v230, v8, vcc
	v_cmp_gt_u32_e32 vcc, s2, v14
	v_subrev_u32_e32 v14, 25, v126
	v_max3_f32 v64, v12, v8, v9
	v_cvt_f32_i32_e32 v13, v14
	v_cvt_f32_i32_e32 v12, v65
	v_pk_fma_f32 v[10:11], v[100:101], v[10:11], v[74:75]
	v_subrev_u32_e32 v66, 27, v126
	v_cndmask_b32_e32 v11, v230, v11, vcc
	v_cmp_gt_u32_e32 vcc, s2, v15
	v_subrev_u32_e32 v67, 26, v126
	v_cvt_f32_i32_e32 v15, v66
	v_cndmask_b32_e32 v10, v230, v10, vcc
	v_cmp_gt_u32_e32 vcc, s2, v14
	v_cvt_f32_i32_e32 v14, v67
	v_pk_fma_f32 v[12:13], v[100:101], v[12:13], v[76:77]
	v_max3_f32 v64, v64, v10, v11
	v_cndmask_b32_e32 v13, v230, v13, vcc
	v_cmp_gt_u32_e32 vcc, s2, v65
	v_subrev_u32_e32 v69, 33, v126
	v_pk_fma_f32 v[14:15], v[100:101], v[14:15], v[78:79]
	v_cndmask_b32_e32 v12, v230, v12, vcc
	v_cmp_gt_u32_e32 vcc, s2, v66
	v_subrev_u32_e32 v66, 32, v126
	v_max3_f32 v68, v64, v12, v13
	v_cvt_f32_i32_e32 v64, v66
	v_cvt_f32_i32_e32 v65, v69
	v_cndmask_b32_e32 v15, v230, v15, vcc
	v_cmp_gt_u32_e32 vcc, s2, v67
	v_pk_fma_f32 v[48:49], v[100:101], v[64:65], v[48:49]
	s_nop 0
	v_cndmask_b32_e32 v14, v230, v14, vcc
	v_max3_f32 v67, v68, v14, v15
	v_cmp_gt_u32_e32 vcc, s2, v69
	v_subrev_u32_e32 v68, 35, v126
	v_subrev_u32_e32 v69, 34, v126
	v_cvt_f32_i32_e32 v65, v68
	v_cvt_f32_i32_e32 v64, v69
	v_cndmask_b32_e32 v103, v230, v49, vcc
	v_cmp_gt_u32_e32 vcc, s2, v66
	s_nop 1
	v_cndmask_b32_e32 v102, v230, v48, vcc
	v_pk_fma_f32 v[48:49], v[100:101], v[64:65], v[50:51]
	v_subrev_u32_e32 v64, 41, v126
	v_subrev_u32_e32 v65, 40, v126
	v_cvt_f32_i32_e32 v51, v64
	v_cvt_f32_i32_e32 v50, v65
	v_cmp_gt_u32_e32 vcc, s2, v68
	v_max3_f32 v66, v67, v102, v103
	s_nop 0
	v_cndmask_b32_e32 v105, v230, v49, vcc
	v_cmp_gt_u32_e32 vcc, s2, v69
	s_nop 1
	v_cndmask_b32_e32 v104, v230, v48, vcc
	v_pk_fma_f32 v[48:49], v[100:101], v[50:51], v[52:53]
	v_subrev_u32_e32 v52, 43, v126
	v_subrev_u32_e32 v53, 42, v126
	v_cvt_f32_i32_e32 v51, v52
	v_cvt_f32_i32_e32 v50, v53
	v_cmp_gt_u32_e32 vcc, s2, v64
	v_max3_f32 v66, v66, v104, v105
	s_nop 0
	v_cndmask_b32_e32 v107, v230, v49, vcc
	v_cmp_gt_u32_e32 vcc, s2, v65
	s_nop 1
	v_cndmask_b32_e32 v106, v230, v48, vcc
	v_pk_fma_f32 v[48:49], v[100:101], v[50:51], v[54:55]
	v_cmp_gt_u32_e32 vcc, s2, v52
	v_subrev_u32_e32 v52, 49, v126
	v_subrev_u32_e32 v54, 48, v126
	v_cvt_f32_i32_e32 v51, v52
	v_cvt_f32_i32_e32 v50, v54
	v_cndmask_b32_e32 v109, v230, v49, vcc
	v_cmp_gt_u32_e32 vcc, s2, v53
	v_subrev_u32_e32 v55, 50, v126
	v_max3_f32 v64, v66, v106, v107
	v_cndmask_b32_e32 v108, v230, v48, vcc
	v_cmp_gt_u32_e32 vcc, s2, v52
	v_subrev_u32_e32 v52, 51, v126
	v_pk_fma_f32 v[48:49], v[100:101], v[50:51], v[56:57]
	v_cvt_f32_i32_e32 v51, v52
	v_cvt_f32_i32_e32 v50, v55
	v_cndmask_b32_e32 v111, v230, v49, vcc
	v_cmp_gt_u32_e32 vcc, s2, v54
	v_subrev_u32_e32 v54, 56, v126
	v_max3_f32 v53, v64, v108, v109
	v_cndmask_b32_e32 v110, v230, v48, vcc
	v_cmp_gt_u32_e32 vcc, s2, v52
	v_subrev_u32_e32 v52, 57, v126
	v_pk_fma_f32 v[48:49], v[100:101], v[50:51], v[58:59]
	v_cvt_f32_i32_e32 v51, v52
	v_cvt_f32_i32_e32 v50, v54
	v_cndmask_b32_e32 v113, v230, v49, vcc
	v_cmp_gt_u32_e32 vcc, s2, v55
	v_subrev_u32_e32 v55, 58, v126
	v_max3_f32 v53, v53, v110, v111
	v_cndmask_b32_e32 v112, v230, v48, vcc
	v_cmp_gt_u32_e32 vcc, s2, v52
	v_subrev_u32_e32 v52, 59, v126
	v_pk_fma_f32 v[48:49], v[100:101], v[50:51], v[60:61]
	v_cvt_f32_i32_e32 v51, v52
	v_cvt_f32_i32_e32 v50, v55
	v_cndmask_b32_e32 v115, v230, v49, vcc
	v_cmp_gt_u32_e32 vcc, s2, v54
	v_max3_f32 v53, v53, v112, v113
	s_nop 0
	v_cndmask_b32_e32 v114, v230, v48, vcc
	v_pk_fma_f32 v[48:49], v[100:101], v[50:51], v[62:63]
	v_cmp_gt_u32_e32 vcc, s2, v52
	v_and_b32_e32 v50, 64, v229
	v_add_u32_e32 v50, 64, v50
	v_cndmask_b32_e32 v117, v230, v49, vcc
	v_cmp_gt_u32_e32 vcc, s2, v55
	v_xor_b32_e32 v49, 32, v229
	v_max3_f32 v53, v53, v114, v115
	v_cndmask_b32_e32 v116, v230, v48, vcc
	v_cmp_lt_i32_e32 vcc, v49, v50
	v_max3_f32 v48, v53, v116, v117
	s_nop 0
	v_cndmask_b32_e32 v49, v229, v49, vcc
	v_lshlrev_b32_e32 v49, 2, v49
	v_mov_b32_e32 v49, v48
	s_nop 1
	v_permlane32_swap_b32_e32 v49, v48
	s_waitcnt lgkmcnt(0)
	v_max_f32_e32 v48, v48, v49
	v_add_f32_e32 v49, 0x41000000, v119
	v_cmp_gt_f32_e32 vcc, v48, v49
	s_cbranch_vccz .LBB0_288
; DI float fexp2(float x) { return __builtin_amdgcn_exp2f(x); }
; DI void softmax_step(int tid, int cls, f32x16 (&S)[2], f32x16 (&O)[2], float& m, float& l, int k0, int qpos, float slope2,
;                      int kmul, int kadd, int W, bool extra) {
;     ...
;     if (__any(mx > m + 8.f)) {
;       float mn = fmaxf(m, mx), alpha = fexp2(m - mn);
;       m = mn; l *= alpha;
; #pragma unroll
;       for (int dt = 0; dt < 2; ++dt)
; #pragma unroll
;         for (int i = 0; i < 16; ++i) O[dt][i] *= alpha;
;     }
	v_max_f32_e32 v48, v48, v48
	v_max_f32_e32 v49, v119, v119
	v_max_f32_e32 v49, v49, v48
	v_sub_f32_e32 v48, v119, v49
	v_exp_f32_e32 v48, v48
	v_mov_b32_e32 v119, v49
	v_mul_f32_e32 v120, v120, v48
	v_pk_mul_f32 v[30:31], v[30:31], v[48:49] op_sel_hi:[1,0]
	v_pk_mul_f32 v[28:29], v[28:29], v[48:49] op_sel_hi:[1,0]
	v_pk_mul_f32 v[26:27], v[26:27], v[48:49] op_sel_hi:[1,0]
	v_pk_mul_f32 v[24:25], v[24:25], v[48:49] op_sel_hi:[1,0]
	v_pk_mul_f32 v[22:23], v[22:23], v[48:49] op_sel_hi:[1,0]
	v_pk_mul_f32 v[20:21], v[20:21], v[48:49] op_sel_hi:[1,0]
	v_pk_mul_f32 v[18:19], v[18:19], v[48:49] op_sel_hi:[1,0]
	v_pk_mul_f32 v[16:17], v[16:17], v[48:49] op_sel_hi:[1,0]
	v_pk_mul_f32 v[46:47], v[46:47], v[48:49] op_sel_hi:[1,0]
	v_pk_mul_f32 v[44:45], v[44:45], v[48:49] op_sel_hi:[1,0]
	v_pk_mul_f32 v[42:43], v[42:43], v[48:49] op_sel_hi:[1,0]
	v_pk_mul_f32 v[40:41], v[40:41], v[48:49] op_sel_hi:[1,0]
	v_pk_mul_f32 v[38:39], v[38:39], v[48:49] op_sel_hi:[1,0]
	v_pk_mul_f32 v[36:37], v[36:37], v[48:49] op_sel_hi:[1,0]
	v_pk_mul_f32 v[34:35], v[34:35], v[48:49] op_sel_hi:[1,0]
	v_pk_mul_f32 v[32:33], v[32:33], v[48:49] op_sel_hi:[1,0]
	s_branch .LBB0_288

; DI float fexp2(float x) { return __builtin_amdgcn_exp2f(x); }
; DI void softmax_step(int tid, int cls, f32x16 (&S)[2], f32x16 (&O)[2], float& m, float& l, int k0, int qpos, float slope2,
;                      int kmul, int kadd, int W, bool extra) {
;     ...
;     mx += b0;
;     mx = fmaxf(mx, __shfl_xor(mx, 32));
;     if (__any(mx > m + 8.f)) {
;       float mn = fmaxf(m, mx), alpha = fexp2(m - mn);
;       m = mn; l *= alpha;
; #pragma unroll
;       for (int dt = 0; dt < 2; ++dt)
; #pragma unroll
;         for (int i = 0; i < 16; ++i) O[dt][i] *= alpha;
;     }
.LBB0_519:
	s_or_b64 exec, exec, s[0:1]
	s_nop 0
	v_cvt_f32_i32_e32 v48, v136
	v_and_b32_e32 v50, 64, v229
	v_xor_b32_e32 v49, 32, v229
	v_add_u32_e32 v50, 64, v50
	v_cmp_lt_i32_e32 vcc, v49, v50
	v_fma_f32 v51, -v180, v48, v137
	v_add_f32_e32 v50, 0x41000000, v133
	v_cndmask_b32_e32 v49, v229, v49, vcc
	v_lshlrev_b32_e32 v49, 2, v49
	v_mov_b32_e32 v49, v51
	s_nop 1
	v_permlane32_swap_b32_e32 v49, v51
	s_waitcnt lgkmcnt(0)
	v_max_f32_e32 v49, v51, v49
	v_cmp_gt_f32_e32 vcc, v49, v50
	s_cbranch_vccz .LBB0_521
	v_max_f32_e32 v49, v49, v49
	v_max_f32_e32 v50, v133, v133
	v_max_f32_e32 v49, v50, v49
	v_sub_f32_e32 v50, v133, v49
	v_exp_f32_e32 v50, v50
	v_mov_b32_e32 v133, v49
	v_mul_f32_e32 v130, v130, v50
	v_pk_mul_f32 v[46:47], v[46:47], v[50:51] op_sel_hi:[1,0]
	v_pk_mul_f32 v[44:45], v[44:45], v[50:51] op_sel_hi:[1,0]
	v_pk_mul_f32 v[42:43], v[42:43], v[50:51] op_sel_hi:[1,0]
	v_pk_mul_f32 v[40:41], v[40:41], v[50:51] op_sel_hi:[1,0]
	v_pk_mul_f32 v[38:39], v[38:39], v[50:51] op_sel_hi:[1,0]
	v_pk_mul_f32 v[36:37], v[36:37], v[50:51] op_sel_hi:[1,0]
	v_pk_mul_f32 v[34:35], v[34:35], v[50:51] op_sel_hi:[1,0]
	v_pk_mul_f32 v[32:33], v[32:33], v[50:51] op_sel_hi:[1,0]
	v_pk_mul_f32 v[30:31], v[30:31], v[50:51] op_sel_hi:[1,0]
	v_pk_mul_f32 v[28:29], v[28:29], v[50:51] op_sel_hi:[1,0]
	v_pk_mul_f32 v[26:27], v[26:27], v[50:51] op_sel_hi:[1,0]
	v_pk_mul_f32 v[24:25], v[24:25], v[50:51] op_sel_hi:[1,0]
	v_pk_mul_f32 v[22:23], v[22:23], v[50:51] op_sel_hi:[1,0]
	v_pk_mul_f32 v[20:21], v[20:21], v[50:51] op_sel_hi:[1,0]
	v_pk_mul_f32 v[18:19], v[18:19], v[50:51] op_sel_hi:[1,0]
	v_pk_mul_f32 v[16:17], v[16:17], v[50:51] op_sel_hi:[1,0]

; DI void softmax_step(int tid, int cls, f32x16 (&S)[2], f32x16 (&O)[2], float& m, float& l, int k0, int qpos, float slope2,
;                      int kmul, int kadd, int W, bool extra) {
;     ...
;   } else {
; #pragma unroll
;     for (int kt = 0; kt < 2; ++kt)
; #pragma unroll
;       for (int i = 0; i < 16; ++i) {
;         int d = dbase - (kt * 32 + (i & 3) + 8 * (i >> 2)) * kmul;
;         bool valid = extra && ((unsigned)d <= (unsigned)W);
;         float s2 = valid ? fmaf(-slope2, (float)d, S[kt][i]) : NEGB;
;         S[kt][i] = s2;
;         mx = fmaxf(mx, s2);
;       }
;     mx = fmaxf(mx, __shfl_xor(mx, 32));
;     if (__any(mx > m + 8.f)) {
.LBB0_522:
	s_andn2_saveexec_b64 s[0:1], s[16:17]
	s_cbranch_execz .LBB0_526
	v_add_u32_e32 v96, 0x7e0, v138
	v_cvt_f32_i32_e32 v94, v136
	v_cvt_f32_i32_e32 v95, v96
	v_subrev_u32_e32 v97, 32, v136
	v_cmp_gt_u32_e32 vcc, s33, v96
	v_subrev_u32_e32 v96, 48, v136
	v_pk_fma_f32 v[64:65], v[182:183], v[94:95], v[64:65]
	v_cvt_f32_i32_e32 v94, v97
	v_cvt_f32_i32_e32 v95, v96
	v_cndmask_b32_e32 v135, v230, v65, vcc
	v_cmp_gt_u32_e32 vcc, s33, v136
	v_add_u32_e32 v99, 0xffffff70, v136
	s_mov_b32 s2, 0xf149f2ca
	v_cndmask_b32_e32 v134, v230, v64, vcc
	v_cmp_gt_u32_e32 vcc, s33, v96
	v_add_u32_e32 v96, 0xffffff80, v136
	v_pk_fma_f32 v[64:65], v[182:183], v[94:95], v[66:67]
	v_cvt_f32_i32_e32 v67, v99
	v_cvt_f32_i32_e32 v66, v96
	v_cndmask_b32_e32 v95, v230, v65, vcc
	v_cmp_gt_u32_e32 vcc, s33, v97
	v_max3_f32 v98, v134, s2, v135
	s_nop 0
	v_cndmask_b32_e32 v94, v230, v64, vcc
	v_pk_fma_f32 v[64:65], v[182:183], v[66:67], v[68:69]
	v_add_u32_e32 v68, 0xffffff60, v136
	v_add_u32_e32 v69, 0xffffff50, v136
	v_cvt_f32_i32_e32 v67, v69
	v_cvt_f32_i32_e32 v66, v68
	v_cmp_gt_u32_e32 vcc, s33, v99
	v_max3_f32 v98, v98, v94, v95
	s_nop 0
	v_cndmask_b32_e32 v97, v230, v65, vcc
	v_cmp_gt_u32_e32 vcc, s33, v96
	s_nop 1
	v_cndmask_b32_e32 v96, v230, v64, vcc
	v_pk_fma_f32 v[64:65], v[182:183], v[66:67], v[70:71]
	v_cmp_gt_u32_e32 vcc, s33, v69
	v_add_u32_e32 v69, 0xffffff00, v136
	v_add_u32_e32 v70, 0xfffffef0, v136
	v_cvt_f32_i32_e32 v67, v70
	v_cvt_f32_i32_e32 v66, v69
	v_cndmask_b32_e32 v99, v230, v65, vcc
	v_cmp_gt_u32_e32 vcc, s33, v68
	v_max3_f32 v100, v98, v96, v97
	v_add_u32_e32 v71, 0xfffffed0, v136
	v_cndmask_b32_e32 v98, v230, v64, vcc
	v_cmp_gt_u32_e32 vcc, s33, v70
	v_add_u32_e32 v70, 0xfffffee0, v136
	v_pk_fma_f32 v[64:65], v[182:183], v[66:67], v[72:73]
	v_cvt_f32_i32_e32 v67, v71
	v_cvt_f32_i32_e32 v66, v70
	v_cndmask_b32_e32 v101, v230, v65, vcc
	v_cmp_gt_u32_e32 vcc, s33, v69
	v_max3_f32 v68, v100, v98, v99
	v_add_u32_e32 v69, 0xfffffe80, v136
	v_cndmask_b32_e32 v100, v230, v64, vcc
	v_cmp_gt_u32_e32 vcc, s33, v71
	v_add_u32_e32 v71, 0xfffffe70, v136
	v_pk_fma_f32 v[64:65], v[182:183], v[66:67], v[74:75]
	v_cvt_f32_i32_e32 v67, v71
	v_cvt_f32_i32_e32 v66, v69
	v_cndmask_b32_e32 v103, v230, v65, vcc
	v_cmp_gt_u32_e32 vcc, s33, v70
	v_add_u32_e32 v70, 0xfffffe60, v136
	v_max3_f32 v68, v68, v100, v101
	v_cndmask_b32_e32 v102, v230, v64, vcc
	v_cmp_gt_u32_e32 vcc, s33, v71
	v_add_u32_e32 v71, 0xfffffe50, v136
	v_pk_fma_f32 v[64:65], v[182:183], v[66:67], v[76:77]
	v_cvt_f32_i32_e32 v67, v71
	v_cvt_f32_i32_e32 v66, v70
	v_cndmask_b32_e32 v105, v230, v65, vcc
	v_cmp_gt_u32_e32 vcc, s33, v69
	v_add_u32_e32 v69, 0xfffffe00, v136
	v_max3_f32 v68, v68, v102, v103
	v_cndmask_b32_e32 v104, v230, v64, vcc
	v_pk_fma_f32 v[64:65], v[182:183], v[66:67], v[78:79]
	v_cmp_gt_u32_e32 vcc, s33, v71
	v_cvt_f32_i32_e32 v66, v69
	v_max3_f32 v68, v68, v104, v105
	v_cndmask_b32_e32 v107, v230, v65, vcc
	v_add_u32_e32 v65, 0xfffffdf0, v136
	v_cvt_f32_i32_e32 v67, v65
	v_cmp_gt_u32_e32 vcc, s33, v70
	v_pk_fma_f32 v[48:49], v[182:183], v[66:67], v[48:49]
	v_add_u32_e32 v66, 0xfffffde0, v136
	v_add_u32_e32 v67, 0xfffffdd0, v136
	v_cndmask_b32_e32 v106, v230, v64, vcc
	v_cmp_gt_u32_e32 vcc, s33, v65
	v_cvt_f32_i32_e32 v65, v67
	v_cvt_f32_i32_e32 v64, v66
	v_cndmask_b32_e32 v109, v230, v49, vcc
	v_cmp_gt_u32_e32 vcc, s33, v69
	v_max3_f32 v68, v68, v106, v107
	s_nop 0
	v_cndmask_b32_e32 v108, v230, v48, vcc
	v_pk_fma_f32 v[48:49], v[182:183], v[64:65], v[50:51]
	v_add_u32_e32 v64, 0xfffffd80, v136
	v_add_u32_e32 v65, 0xfffffd70, v136
	v_cvt_f32_i32_e32 v51, v65
	v_cvt_f32_i32_e32 v50, v64
	v_cmp_gt_u32_e32 vcc, s33, v67
	v_max3_f32 v68, v68, v108, v109
	s_nop 0
	v_cndmask_b32_e32 v111, v230, v49, vcc
	v_cmp_gt_u32_e32 vcc, s33, v66
	s_nop 1
	v_cndmask_b32_e32 v110, v230, v48, vcc
	v_pk_fma_f32 v[48:49], v[182:183], v[50:51], v[52:53]
	v_add_u32_e32 v52, 0xfffffd60, v136
	v_add_u32_e32 v53, 0xfffffd50, v136
	v_cvt_f32_i32_e32 v51, v53
	v_cvt_f32_i32_e32 v50, v52
	v_cmp_gt_u32_e32 vcc, s33, v65
	v_max3_f32 v66, v68, v110, v111
	s_nop 0
	v_cndmask_b32_e32 v113, v230, v49, vcc
	v_cmp_gt_u32_e32 vcc, s33, v64
	s_nop 1
	v_cndmask_b32_e32 v112, v230, v48, vcc
	v_pk_fma_f32 v[48:49], v[182:183], v[50:51], v[54:55]
	v_cmp_gt_u32_e32 vcc, s33, v53
	v_add_u32_e32 v53, 0xfffffd00, v136
	v_add_u32_e32 v54, 0xfffffcf0, v136
	v_cvt_f32_i32_e32 v51, v54
	v_cvt_f32_i32_e32 v50, v53
	v_cndmask_b32_e32 v115, v230, v49, vcc
	v_cmp_gt_u32_e32 vcc, s33, v52
	v_add_u32_e32 v55, 0xfffffcd0, v136
	v_max3_f32 v64, v66, v112, v113
	v_cndmask_b32_e32 v114, v230, v48, vcc
	v_cmp_gt_u32_e32 vcc, s33, v54
	v_add_u32_e32 v54, 0xfffffce0, v136
	v_pk_fma_f32 v[48:49], v[182:183], v[50:51], v[56:57]
	v_cvt_f32_i32_e32 v51, v55
	v_cvt_f32_i32_e32 v50, v54
	v_cndmask_b32_e32 v117, v230, v49, vcc
	v_cmp_gt_u32_e32 vcc, s33, v53
	v_add_u32_e32 v53, 0xfffffc80, v136
	v_max3_f32 v52, v64, v114, v115
	v_cndmask_b32_e32 v116, v230, v48, vcc
	v_cmp_gt_u32_e32 vcc, s33, v55
	v_add_u32_e32 v55, 0xfffffc70, v136
	v_pk_fma_f32 v[48:49], v[182:183], v[50:51], v[58:59]
	v_cvt_f32_i32_e32 v51, v55
	v_cvt_f32_i32_e32 v50, v53
	v_cndmask_b32_e32 v119, v230, v49, vcc
	v_cmp_gt_u32_e32 vcc, s33, v54
	v_add_u32_e32 v54, 0xfffffc60, v136
	v_max3_f32 v52, v52, v116, v117
	v_cndmask_b32_e32 v118, v230, v48, vcc
	v_cmp_gt_u32_e32 vcc, s33, v55
	v_add_u32_e32 v55, 0xfffffc50, v136
	v_pk_fma_f32 v[48:49], v[182:183], v[50:51], v[60:61]
	v_cvt_f32_i32_e32 v51, v55
	v_cvt_f32_i32_e32 v50, v54
	v_cndmask_b32_e32 v121, v230, v49, vcc
	v_cmp_gt_u32_e32 vcc, s33, v53
	v_max3_f32 v52, v52, v118, v119
	s_nop 0
	v_cndmask_b32_e32 v120, v230, v48, vcc
	v_pk_fma_f32 v[48:49], v[182:183], v[50:51], v[62:63]
	v_cmp_gt_u32_e32 vcc, s33, v55
	v_and_b32_e32 v50, 64, v229
	v_add_u32_e32 v50, 64, v50
	v_cndmask_b32_e32 v123, v230, v49, vcc
	v_cmp_gt_u32_e32 vcc, s33, v54
	v_xor_b32_e32 v49, 32, v229
	v_max3_f32 v52, v52, v120, v121
	v_cndmask_b32_e32 v122, v230, v48, vcc
	v_cmp_lt_i32_e32 vcc, v49, v50
	v_max3_f32 v48, v52, v122, v123
	s_nop 0
	v_cndmask_b32_e32 v49, v229, v49, vcc
	v_lshlrev_b32_e32 v49, 2, v49
	v_mov_b32_e32 v49, v48
	s_nop 1
	v_permlane32_swap_b32_e32 v49, v48
	s_waitcnt lgkmcnt(0)
	v_max_f32_e32 v48, v48, v49
	v_add_f32_e32 v49, 0x41000000, v133
	v_cmp_gt_f32_e32 vcc, v48, v49
	s_cbranch_vccz .LBB0_525
; DI float fexp2(float x) { return __builtin_amdgcn_exp2f(x); }
; DI void softmax_step(int tid, int cls, f32x16 (&S)[2], f32x16 (&O)[2], float& m, float& l, int k0, int qpos, float slope2,
;                      int kmul, int kadd, int W, bool extra) {
;     ...
;     if (__any(mx > m + 8.f)) {
;       float mn = fmaxf(m, mx), alpha = fexp2(m - mn);
;       m = mn; l *= alpha;
; #pragma unroll
;       for (int dt = 0; dt < 2; ++dt)
; #pragma unroll
;         for (int i = 0; i < 16; ++i) O[dt][i] *= alpha;
;     }
	v_max_f32_e32 v48, v48, v48
	v_max_f32_e32 v49, v133, v133
	v_max_f32_e32 v49, v49, v48
	v_sub_f32_e32 v48, v133, v49
	v_exp_f32_e32 v48, v48
	v_mov_b32_e32 v133, v49
	v_mul_f32_e32 v130, v130, v48
	v_pk_mul_f32 v[46:47], v[46:47], v[48:49] op_sel_hi:[1,0]
	v_pk_mul_f32 v[44:45], v[44:45], v[48:49] op_sel_hi:[1,0]
	v_pk_mul_f32 v[42:43], v[42:43], v[48:49] op_sel_hi:[1,0]
	v_pk_mul_f32 v[40:41], v[40:41], v[48:49] op_sel_hi:[1,0]
	v_pk_mul_f32 v[38:39], v[38:39], v[48:49] op_sel_hi:[1,0]
	v_pk_mul_f32 v[36:37], v[36:37], v[48:49] op_sel_hi:[1,0]
	v_pk_mul_f32 v[34:35], v[34:35], v[48:49] op_sel_hi:[1,0]
	v_pk_mul_f32 v[32:33], v[32:33], v[48:49] op_sel_hi:[1,0]
	v_pk_mul_f32 v[30:31], v[30:31], v[48:49] op_sel_hi:[1,0]
	v_pk_mul_f32 v[28:29], v[28:29], v[48:49] op_sel_hi:[1,0]
	v_pk_mul_f32 v[26:27], v[26:27], v[48:49] op_sel_hi:[1,0]
	v_pk_mul_f32 v[24:25], v[24:25], v[48:49] op_sel_hi:[1,0]
	v_pk_mul_f32 v[22:23], v[22:23], v[48:49] op_sel_hi:[1,0]
	v_pk_mul_f32 v[20:21], v[20:21], v[48:49] op_sel_hi:[1,0]
	v_pk_mul_f32 v[18:19], v[18:19], v[48:49] op_sel_hi:[1,0]
	v_pk_mul_f32 v[16:17], v[16:17], v[48:49] op_sel_hi:[1,0]

; DI void softmax_step(int tid, int cls, f32x16 (&S)[2], f32x16 (&O)[2], float& m, float& l, int k0, int qpos, float slope2,
;                      int kmul, int kadd, int W, bool extra) {
;     ...
;   } else {
; #pragma unroll
;     for (int kt = 0; kt < 2; ++kt)
; #pragma unroll
;       for (int i = 0; i < 16; ++i) {
;         int d = dbase - (kt * 32 + (i & 3) + 8 * (i >> 2)) * kmul;
;         bool valid = extra && ((unsigned)d <= (unsigned)W);
;         float s2 = valid ? fmaf(-slope2, (float)d, S[kt][i]) : NEGB;
;         S[kt][i] = s2;
;         mx = fmaxf(mx, s2);
;       }
;     mx = fmaxf(mx, __shfl_xor(mx, 32));
;     if (__any(mx > m + 8.f)) {
.LBB0_551:
	s_andn2_saveexec_b64 s[0:1], s[16:17]
	s_cbranch_execz .LBB0_555
	v_add_u32_e32 v96, 0x3e0, v138
	v_cvt_f32_i32_e32 v94, v136
	v_cvt_f32_i32_e32 v95, v96
	v_subrev_u32_e32 v97, 32, v136
	v_cmp_gt_u32_e32 vcc, s33, v96
	v_subrev_u32_e32 v96, 48, v136
	v_pk_fma_f32 v[64:65], v[182:183], v[94:95], v[64:65]
	v_cvt_f32_i32_e32 v94, v97
	v_cvt_f32_i32_e32 v95, v96
	v_cndmask_b32_e32 v135, v230, v65, vcc
	v_cmp_gt_u32_e32 vcc, s33, v136
	v_add_u32_e32 v99, 0xffffff70, v136
	s_mov_b32 s2, 0xf149f2ca
	v_cndmask_b32_e32 v134, v230, v64, vcc
	v_cmp_gt_u32_e32 vcc, s33, v96
	v_add_u32_e32 v96, 0xffffff80, v136
	v_pk_fma_f32 v[64:65], v[182:183], v[94:95], v[66:67]
	v_cvt_f32_i32_e32 v67, v99
	v_cvt_f32_i32_e32 v66, v96
	v_cndmask_b32_e32 v95, v230, v65, vcc
	v_cmp_gt_u32_e32 vcc, s33, v97
	v_max3_f32 v98, v134, s2, v135
	s_nop 0
	v_cndmask_b32_e32 v94, v230, v64, vcc
	v_pk_fma_f32 v[64:65], v[182:183], v[66:67], v[68:69]
	v_add_u32_e32 v68, 0xffffff60, v136
	v_add_u32_e32 v69, 0xffffff50, v136
	v_cvt_f32_i32_e32 v67, v69
	v_cvt_f32_i32_e32 v66, v68
	v_cmp_gt_u32_e32 vcc, s33, v99
	v_max3_f32 v98, v98, v94, v95
	s_nop 0
	v_cndmask_b32_e32 v97, v230, v65, vcc
	v_cmp_gt_u32_e32 vcc, s33, v96
	s_nop 1
	v_cndmask_b32_e32 v96, v230, v64, vcc
	v_pk_fma_f32 v[64:65], v[182:183], v[66:67], v[70:71]
	v_cmp_gt_u32_e32 vcc, s33, v69
	v_add_u32_e32 v69, 0xffffff00, v136
	v_add_u32_e32 v70, 0xfffffef0, v136
	v_cvt_f32_i32_e32 v67, v70
	v_cvt_f32_i32_e32 v66, v69
	v_cndmask_b32_e32 v99, v230, v65, vcc
	v_cmp_gt_u32_e32 vcc, s33, v68
	v_max3_f32 v100, v98, v96, v97
	v_add_u32_e32 v71, 0xfffffed0, v136
	v_cndmask_b32_e32 v98, v230, v64, vcc
	v_cmp_gt_u32_e32 vcc, s33, v70
	v_add_u32_e32 v70, 0xfffffee0, v136
	v_pk_fma_f32 v[64:65], v[182:183], v[66:67], v[72:73]
	v_cvt_f32_i32_e32 v67, v71
	v_cvt_f32_i32_e32 v66, v70
	v_cndmask_b32_e32 v101, v230, v65, vcc
	v_cmp_gt_u32_e32 vcc, s33, v69
	v_max3_f32 v68, v100, v98, v99
	v_add_u32_e32 v69, 0xfffffe80, v136
	v_cndmask_b32_e32 v100, v230, v64, vcc
	v_cmp_gt_u32_e32 vcc, s33, v71
	v_add_u32_e32 v71, 0xfffffe70, v136
	v_pk_fma_f32 v[64:65], v[182:183], v[66:67], v[74:75]
	v_cvt_f32_i32_e32 v67, v71
	v_cvt_f32_i32_e32 v66, v69
	v_cndmask_b32_e32 v103, v230, v65, vcc
	v_cmp_gt_u32_e32 vcc, s33, v70
	v_add_u32_e32 v70, 0xfffffe60, v136
	v_max3_f32 v68, v68, v100, v101
	v_cndmask_b32_e32 v102, v230, v64, vcc
	v_cmp_gt_u32_e32 vcc, s33, v71
	v_add_u32_e32 v71, 0xfffffe50, v136
	v_pk_fma_f32 v[64:65], v[182:183], v[66:67], v[76:77]
	v_cvt_f32_i32_e32 v67, v71
	v_cvt_f32_i32_e32 v66, v70
	v_cndmask_b32_e32 v105, v230, v65, vcc
	v_cmp_gt_u32_e32 vcc, s33, v69
	v_add_u32_e32 v69, 0xfffffe00, v136
	v_max3_f32 v68, v68, v102, v103
	v_cndmask_b32_e32 v104, v230, v64, vcc
	v_pk_fma_f32 v[64:65], v[182:183], v[66:67], v[78:79]
	v_cmp_gt_u32_e32 vcc, s33, v71
	v_cvt_f32_i32_e32 v66, v69
	v_max3_f32 v68, v68, v104, v105
	v_cndmask_b32_e32 v107, v230, v65, vcc
	v_add_u32_e32 v65, 0xfffffdf0, v136
	v_cvt_f32_i32_e32 v67, v65
	v_cmp_gt_u32_e32 vcc, s33, v70
	v_pk_fma_f32 v[48:49], v[182:183], v[66:67], v[48:49]
	v_add_u32_e32 v66, 0xfffffde0, v136
	v_add_u32_e32 v67, 0xfffffdd0, v136
	v_cndmask_b32_e32 v106, v230, v64, vcc
	v_cmp_gt_u32_e32 vcc, s33, v65
	v_cvt_f32_i32_e32 v65, v67
	v_cvt_f32_i32_e32 v64, v66
	v_cndmask_b32_e32 v109, v230, v49, vcc
	v_cmp_gt_u32_e32 vcc, s33, v69
	v_max3_f32 v68, v68, v106, v107
	s_nop 0
	v_cndmask_b32_e32 v108, v230, v48, vcc
	v_pk_fma_f32 v[48:49], v[182:183], v[64:65], v[50:51]
	v_add_u32_e32 v64, 0xfffffd80, v136
	v_add_u32_e32 v65, 0xfffffd70, v136
	v_cvt_f32_i32_e32 v51, v65
	v_cvt_f32_i32_e32 v50, v64
	v_cmp_gt_u32_e32 vcc, s33, v67
	v_max3_f32 v68, v68, v108, v109
	s_nop 0
	v_cndmask_b32_e32 v111, v230, v49, vcc
	v_cmp_gt_u32_e32 vcc, s33, v66
	s_nop 1
	v_cndmask_b32_e32 v110, v230, v48, vcc
	v_pk_fma_f32 v[48:49], v[182:183], v[50:51], v[52:53]
	v_add_u32_e32 v52, 0xfffffd60, v136
	v_add_u32_e32 v53, 0xfffffd50, v136
	v_cvt_f32_i32_e32 v51, v53
	v_cvt_f32_i32_e32 v50, v52
	v_cmp_gt_u32_e32 vcc, s33, v65
	v_max3_f32 v66, v68, v110, v111
	s_nop 0
	v_cndmask_b32_e32 v113, v230, v49, vcc
	v_cmp_gt_u32_e32 vcc, s33, v64
	s_nop 1
	v_cndmask_b32_e32 v112, v230, v48, vcc
	v_pk_fma_f32 v[48:49], v[182:183], v[50:51], v[54:55]
	v_cmp_gt_u32_e32 vcc, s33, v53
	v_add_u32_e32 v53, 0xfffffd00, v136
	v_add_u32_e32 v54, 0xfffffcf0, v136
	v_cvt_f32_i32_e32 v51, v54
	v_cvt_f32_i32_e32 v50, v53
	v_cndmask_b32_e32 v115, v230, v49, vcc
	v_cmp_gt_u32_e32 vcc, s33, v52
	v_add_u32_e32 v55, 0xfffffcd0, v136
	v_max3_f32 v64, v66, v112, v113
	v_cndmask_b32_e32 v114, v230, v48, vcc
	v_cmp_gt_u32_e32 vcc, s33, v54
	v_add_u32_e32 v54, 0xfffffce0, v136
	v_pk_fma_f32 v[48:49], v[182:183], v[50:51], v[56:57]
	v_cvt_f32_i32_e32 v51, v55
	v_cvt_f32_i32_e32 v50, v54
	v_cndmask_b32_e32 v117, v230, v49, vcc
	v_cmp_gt_u32_e32 vcc, s33, v53
	v_add_u32_e32 v53, 0xfffffc80, v136
	v_max3_f32 v52, v64, v114, v115
	v_cndmask_b32_e32 v116, v230, v48, vcc
	v_cmp_gt_u32_e32 vcc, s33, v55
	v_add_u32_e32 v55, 0xfffffc70, v136
	v_pk_fma_f32 v[48:49], v[182:183], v[50:51], v[58:59]
	v_cvt_f32_i32_e32 v51, v55
	v_cvt_f32_i32_e32 v50, v53
	v_cndmask_b32_e32 v119, v230, v49, vcc
	v_cmp_gt_u32_e32 vcc, s33, v54
	v_add_u32_e32 v54, 0xfffffc60, v136
	v_max3_f32 v52, v52, v116, v117
	v_cndmask_b32_e32 v118, v230, v48, vcc
	v_cmp_gt_u32_e32 vcc, s33, v55
	v_add_u32_e32 v55, 0xfffffc50, v136
	v_pk_fma_f32 v[48:49], v[182:183], v[50:51], v[60:61]
	v_cvt_f32_i32_e32 v51, v55
	v_cvt_f32_i32_e32 v50, v54
	v_cndmask_b32_e32 v121, v230, v49, vcc
	v_cmp_gt_u32_e32 vcc, s33, v53
	v_max3_f32 v52, v52, v118, v119
	s_nop 0
	v_cndmask_b32_e32 v120, v230, v48, vcc
	v_pk_fma_f32 v[48:49], v[182:183], v[50:51], v[62:63]
	v_cmp_gt_u32_e32 vcc, s33, v55
	v_and_b32_e32 v50, 64, v229
	v_add_u32_e32 v50, 64, v50
	v_cndmask_b32_e32 v123, v230, v49, vcc
	v_cmp_gt_u32_e32 vcc, s33, v54
	v_xor_b32_e32 v49, 32, v229
	v_max3_f32 v52, v52, v120, v121
	v_cndmask_b32_e32 v122, v230, v48, vcc
	v_cmp_lt_i32_e32 vcc, v49, v50
	v_max3_f32 v48, v52, v122, v123
	s_nop 0
	v_cndmask_b32_e32 v49, v229, v49, vcc
	v_lshlrev_b32_e32 v49, 2, v49
	v_mov_b32_e32 v49, v48
	s_nop 1
	v_permlane32_swap_b32_e32 v49, v48
	s_waitcnt lgkmcnt(0)
	v_max_f32_e32 v48, v48, v49
	v_add_f32_e32 v49, 0x41000000, v133
	v_cmp_gt_f32_e32 vcc, v48, v49
	s_cbranch_vccz .LBB0_554
; DI float fexp2(float x) { return __builtin_amdgcn_exp2f(x); }
; DI void softmax_step(int tid, int cls, f32x16 (&S)[2], f32x16 (&O)[2], float& m, float& l, int k0, int qpos, float slope2,
;                      int kmul, int kadd, int W, bool extra) {
;     ...
;     if (__any(mx > m + 8.f)) {
;       float mn = fmaxf(m, mx), alpha = fexp2(m - mn);
;       m = mn; l *= alpha;
; #pragma unroll
;       for (int dt = 0; dt < 2; ++dt)
; #pragma unroll
;         for (int i = 0; i < 16; ++i) O[dt][i] *= alpha;
;     }
	v_max_f32_e32 v48, v48, v48
	v_max_f32_e32 v49, v133, v133
	v_max_f32_e32 v49, v49, v48
	v_sub_f32_e32 v48, v133, v49
	v_exp_f32_e32 v48, v48
	v_mov_b32_e32 v133, v49
	v_mul_f32_e32 v130, v130, v48
	v_pk_mul_f32 v[46:47], v[46:47], v[48:49] op_sel_hi:[1,0]
	v_pk_mul_f32 v[44:45], v[44:45], v[48:49] op_sel_hi:[1,0]
	v_pk_mul_f32 v[42:43], v[42:43], v[48:49] op_sel_hi:[1,0]
	v_pk_mul_f32 v[40:41], v[40:41], v[48:49] op_sel_hi:[1,0]
	v_pk_mul_f32 v[38:39], v[38:39], v[48:49] op_sel_hi:[1,0]
	v_pk_mul_f32 v[36:37], v[36:37], v[48:49] op_sel_hi:[1,0]
	v_pk_mul_f32 v[34:35], v[34:35], v[48:49] op_sel_hi:[1,0]
	v_pk_mul_f32 v[32:33], v[32:33], v[48:49] op_sel_hi:[1,0]
	v_pk_mul_f32 v[30:31], v[30:31], v[48:49] op_sel_hi:[1,0]
	v_pk_mul_f32 v[28:29], v[28:29], v[48:49] op_sel_hi:[1,0]
	v_pk_mul_f32 v[26:27], v[26:27], v[48:49] op_sel_hi:[1,0]
	v_pk_mul_f32 v[24:25], v[24:25], v[48:49] op_sel_hi:[1,0]
	v_pk_mul_f32 v[22:23], v[22:23], v[48:49] op_sel_hi:[1,0]
	v_pk_mul_f32 v[20:21], v[20:21], v[48:49] op_sel_hi:[1,0]
	v_pk_mul_f32 v[18:19], v[18:19], v[48:49] op_sel_hi:[1,0]
	v_pk_mul_f32 v[16:17], v[16:17], v[48:49] op_sel_hi:[1,0]

; DI float fexp2(float x) { return __builtin_amdgcn_exp2f(x); }
; DI void softmax_step(int tid, int cls, f32x16 (&S)[2], f32x16 (&O)[2], float& m, float& l, int k0, int qpos, float slope2,
;                      int kmul, int kadd, int W, bool extra) {
;     ...
;     mx += b0;
;     mx = fmaxf(mx, __shfl_xor(mx, 32));
;     if (__any(mx > m + 8.f)) {
;       float mn = fmaxf(m, mx), alpha = fexp2(m - mn);
;       m = mn; l *= alpha;
; #pragma unroll
;       for (int dt = 0; dt < 2; ++dt)
; #pragma unroll
;         for (int i = 0; i < 16; ++i) O[dt][i] *= alpha;
;     }
.LBB0_629:
	s_or_b64 exec, exec, s[2:3]
	s_nop 1
	v_fma_f32 v96, -v180, v172, v173
	v_mov_b32_e32 v97, v96
	s_nop 1
	v_permlane32_swap_b32_e32 v97, v96
	s_waitcnt lgkmcnt(0)
	v_max_f32_e32 v96, v96, v97
	v_add_f32_e32 v97, 0x41000000, v170
	v_cmp_gt_f32_e32 vcc, v96, v97
	s_cbranch_vccz .LBB0_631
	v_max_f32_e32 v96, v96, v96
	v_max_f32_e32 v97, v170, v170
	v_max_f32_e32 v97, v97, v96
	v_sub_f32_e32 v96, v170, v97
	v_exp_f32_e32 v96, v96
	v_mov_b32_e32 v170, v97
	v_mul_f32_e32 v214, v214, v96
	v_pk_mul_f32 v[78:79], v[78:79], v[96:97] op_sel_hi:[1,0]
	v_pk_mul_f32 v[76:77], v[76:77], v[96:97] op_sel_hi:[1,0]
	v_pk_mul_f32 v[74:75], v[74:75], v[96:97] op_sel_hi:[1,0]
	v_pk_mul_f32 v[72:73], v[72:73], v[96:97] op_sel_hi:[1,0]
	v_pk_mul_f32 v[70:71], v[70:71], v[96:97] op_sel_hi:[1,0]
	v_pk_mul_f32 v[68:69], v[68:69], v[96:97] op_sel_hi:[1,0]
	v_pk_mul_f32 v[66:67], v[66:67], v[96:97] op_sel_hi:[1,0]
	v_pk_mul_f32 v[64:65], v[64:65], v[96:97] op_sel_hi:[1,0]
	v_pk_mul_f32 v[62:63], v[62:63], v[96:97] op_sel_hi:[1,0]
	v_pk_mul_f32 v[60:61], v[60:61], v[96:97] op_sel_hi:[1,0]
	v_pk_mul_f32 v[58:59], v[58:59], v[96:97] op_sel_hi:[1,0]
	v_pk_mul_f32 v[56:57], v[56:57], v[96:97] op_sel_hi:[1,0]
	v_pk_mul_f32 v[54:55], v[54:55], v[96:97] op_sel_hi:[1,0]
	v_pk_mul_f32 v[52:53], v[52:53], v[96:97] op_sel_hi:[1,0]
	v_pk_mul_f32 v[50:51], v[50:51], v[96:97] op_sel_hi:[1,0]
	v_pk_mul_f32 v[48:49], v[48:49], v[96:97] op_sel_hi:[1,0]

; DI void softmax_step(int tid, int cls, f32x16 (&S)[2], f32x16 (&O)[2], float& m, float& l, int k0, int qpos, float slope2,
;                      int kmul, int kadd, int W, bool extra) {
;     ...
; #pragma unroll
;     for (int kt = 0; kt < 2; ++kt)
; #pragma unroll
;       for (int i = 0; i < 16; ++i) {
;         int d = dbase - (kt * 32 + (i & 3) + 8 * (i >> 2)) * kmul;
;         bool valid = extra && ((unsigned)d <= (unsigned)W);
;         float s2 = valid ? fmaf(-slope2, (float)d, S[kt][i]) : NEGB;
;         S[kt][i] = s2;
;         mx = fmaxf(mx, s2);
;       }
;     mx = fmaxf(mx, __shfl_xor(mx, 32));
;     if (__any(mx > m + 8.f)) {
.LBB0_632:
	s_andn2_saveexec_b64 s[8:9], s[0:1]
	s_cbranch_execz .LBB0_636
	v_cmp_gt_u32_e32 vcc, s33, v171
	s_and_b64 vcc, vcc, s[36:37]
	v_fma_f32 v80, -v180, v172, v128
	v_add_u32_e32 v81, -1, v171
	v_cndmask_b32_e32 v80, v230, v80, vcc
	v_cmp_gt_u32_e32 vcc, s33, v81
	v_cvt_f32_i32_e32 v81, v81
	s_and_b64 vcc, s[36:37], vcc
	v_add_u32_e32 v82, -2, v171
	v_add_u32_e32 v83, -3, v171
	v_fma_f32 v81, -v180, v81, v129
	v_cndmask_b32_e32 v81, v230, v81, vcc
	v_cmp_gt_u32_e32 vcc, s33, v82
	v_cvt_f32_i32_e32 v82, v82
	s_and_b64 vcc, s[36:37], vcc
	s_mov_b32 s0, 0xf149f2ca
	v_max3_f32 v84, v80, s0, v81
	v_fma_f32 v82, -v180, v82, v130
	v_cndmask_b32_e32 v82, v230, v82, vcc
	v_cmp_gt_u32_e32 vcc, s33, v83
	v_cvt_f32_i32_e32 v83, v83
	s_and_b64 vcc, vcc, s[36:37]
	v_add_u32_e32 v85, -9, v171
	v_add_u32_e32 v87, -11, v171
	v_fma_f32 v83, -v180, v83, v131
	v_cndmask_b32_e32 v83, v230, v83, vcc
	v_max3_f32 v86, v84, v82, v83
	v_add_u32_e32 v84, -8, v171
	v_cmp_gt_u32_e32 vcc, s33, v84
	v_cvt_f32_i32_e32 v84, v84
	s_and_b64 vcc, s[36:37], vcc
	v_subrev_u32_e32 v89, 17, v171
	v_subrev_u32_e32 v91, 19, v171
	v_fma_f32 v84, -v180, v84, v132
	v_cndmask_b32_e32 v84, v230, v84, vcc
	v_cmp_gt_u32_e32 vcc, s33, v85
	v_cvt_f32_i32_e32 v85, v85
	s_and_b64 vcc, vcc, s[36:37]
	v_subrev_u32_e32 v93, 25, v171
	v_subrev_u32_e32 v95, 27, v171
	v_fma_f32 v85, -v180, v85, v133
	v_cndmask_b32_e32 v85, v230, v85, vcc
	v_max3_f32 v88, v86, v84, v85
	v_add_u32_e32 v86, -10, v171
	v_cmp_gt_u32_e32 vcc, s33, v86
	v_cvt_f32_i32_e32 v86, v86
	s_and_b64 vcc, vcc, s[36:37]
	v_fma_f32 v86, -v180, v86, v134
	v_cndmask_b32_e32 v86, v230, v86, vcc
	v_cmp_gt_u32_e32 vcc, s33, v87
	v_cvt_f32_i32_e32 v87, v87
	s_and_b64 vcc, vcc, s[36:37]
	v_fma_f32 v87, -v180, v87, v135
	v_cndmask_b32_e32 v87, v230, v87, vcc
	v_max3_f32 v90, v88, v86, v87
	v_add_u32_e32 v88, -16, v171
	v_cmp_gt_u32_e32 vcc, s33, v88
	v_cvt_f32_i32_e32 v88, v88
	s_and_b64 vcc, s[36:37], vcc
	v_fma_f32 v88, -v180, v88, v136
	v_cndmask_b32_e32 v88, v230, v88, vcc
	v_cmp_gt_u32_e32 vcc, s33, v89
	v_cvt_f32_i32_e32 v89, v89
	s_and_b64 vcc, vcc, s[36:37]
	v_fma_f32 v89, -v180, v89, v137
	v_cndmask_b32_e32 v89, v230, v89, vcc
	v_max3_f32 v92, v90, v88, v89
	v_subrev_u32_e32 v90, 18, v171
	v_cmp_gt_u32_e32 vcc, s33, v90
	v_cvt_f32_i32_e32 v90, v90
	s_and_b64 vcc, vcc, s[36:37]
	v_fma_f32 v90, -v180, v90, v138
	v_cndmask_b32_e32 v90, v230, v90, vcc
	v_cmp_gt_u32_e32 vcc, s33, v91
	v_cvt_f32_i32_e32 v91, v91
	s_and_b64 vcc, vcc, s[36:37]
	v_fma_f32 v91, -v180, v91, v139
	v_cndmask_b32_e32 v91, v230, v91, vcc
	v_max3_f32 v94, v92, v90, v91
	v_subrev_u32_e32 v92, 24, v171
	v_cmp_gt_u32_e32 vcc, s33, v92
	v_cvt_f32_i32_e32 v92, v92
	s_and_b64 vcc, vcc, s[36:37]
	v_fma_f32 v92, -v180, v92, v140
	v_cndmask_b32_e32 v92, v230, v92, vcc
	v_cmp_gt_u32_e32 vcc, s33, v93
	v_cvt_f32_i32_e32 v93, v93
	s_and_b64 vcc, vcc, s[36:37]
	v_fma_f32 v93, -v180, v93, v141
	v_cndmask_b32_e32 v93, v230, v93, vcc
	v_max3_f32 v112, v94, v92, v93
	v_subrev_u32_e32 v94, 26, v171
	v_cmp_gt_u32_e32 vcc, s33, v94
	v_cvt_f32_i32_e32 v94, v94
	s_and_b64 vcc, vcc, s[36:37]
	v_fma_f32 v94, -v180, v94, v142
	v_cndmask_b32_e32 v94, v230, v94, vcc
	v_cmp_gt_u32_e32 vcc, s33, v95
	v_cvt_f32_i32_e32 v95, v95
	s_and_b64 vcc, vcc, s[36:37]
	v_fma_f32 v95, -v180, v95, v143
	v_cndmask_b32_e32 v95, v230, v95, vcc
	v_max3_f32 v114, v112, v94, v95
	v_subrev_u32_e32 v112, 32, v171
	v_cmp_gt_u32_e32 vcc, s33, v112
	v_cvt_f32_i32_e32 v112, v112
	s_and_b64 vcc, s[36:37], vcc
	v_fma_f32 v96, -v180, v112, v96
	v_cndmask_b32_e32 v112, v230, v96, vcc
	v_subrev_u32_e32 v96, 33, v171
	v_cmp_gt_u32_e32 vcc, s33, v96
	v_cvt_f32_i32_e32 v96, v96
	s_and_b64 vcc, vcc, s[36:37]
	v_fma_f32 v96, -v180, v96, v97
	v_subrev_u32_e32 v97, 34, v171
	v_cndmask_b32_e32 v113, v230, v96, vcc
	v_cmp_gt_u32_e32 vcc, s33, v97
	v_cvt_f32_i32_e32 v97, v97
	s_and_b64 vcc, vcc, s[36:37]
	v_max3_f32 v96, v114, v112, v113
	v_fma_f32 v97, -v180, v97, v98
	v_cndmask_b32_e32 v114, v230, v97, vcc
	v_subrev_u32_e32 v97, 35, v171
	v_cmp_gt_u32_e32 vcc, s33, v97
	v_cvt_f32_i32_e32 v97, v97
	s_and_b64 vcc, vcc, s[36:37]
	v_fma_f32 v97, -v180, v97, v99
	v_cndmask_b32_e32 v115, v230, v97, vcc
	v_subrev_u32_e32 v97, 40, v171
	v_cmp_gt_u32_e32 vcc, s33, v97
	v_cvt_f32_i32_e32 v97, v97
	s_and_b64 vcc, vcc, s[36:37]
	v_max3_f32 v96, v96, v114, v115
	v_fma_f32 v97, -v180, v97, v100
	v_cndmask_b32_e32 v116, v230, v97, vcc
	v_subrev_u32_e32 v97, 41, v171
	v_cmp_gt_u32_e32 vcc, s33, v97
	v_cvt_f32_i32_e32 v97, v97
	s_and_b64 vcc, vcc, s[36:37]
	v_fma_f32 v97, -v180, v97, v101
	v_cndmask_b32_e32 v117, v230, v97, vcc
	v_subrev_u32_e32 v97, 42, v171
	v_cmp_gt_u32_e32 vcc, s33, v97
	v_cvt_f32_i32_e32 v97, v97
	s_and_b64 vcc, vcc, s[36:37]
	v_max3_f32 v96, v96, v116, v117
	v_fma_f32 v97, -v180, v97, v102
	v_cndmask_b32_e32 v118, v230, v97, vcc
	v_subrev_u32_e32 v97, 43, v171
	v_cmp_gt_u32_e32 vcc, s33, v97
	v_cvt_f32_i32_e32 v97, v97
	s_and_b64 vcc, vcc, s[36:37]
	v_fma_f32 v97, -v180, v97, v103
	v_cndmask_b32_e32 v119, v230, v97, vcc
	v_subrev_u32_e32 v97, 48, v171
	v_cmp_gt_u32_e32 vcc, s33, v97
	v_cvt_f32_i32_e32 v97, v97
	s_and_b64 vcc, vcc, s[36:37]
	v_max3_f32 v96, v96, v118, v119
	v_fma_f32 v97, -v180, v97, v104
	v_cndmask_b32_e32 v120, v230, v97, vcc
	v_subrev_u32_e32 v97, 49, v171
	v_cmp_gt_u32_e32 vcc, s33, v97
	v_cvt_f32_i32_e32 v97, v97
	s_and_b64 vcc, vcc, s[36:37]
	v_fma_f32 v97, -v180, v97, v105
	v_cndmask_b32_e32 v121, v230, v97, vcc
	v_subrev_u32_e32 v97, 50, v171
	v_cmp_gt_u32_e32 vcc, s33, v97
	v_cvt_f32_i32_e32 v97, v97
	s_and_b64 vcc, vcc, s[36:37]
	v_max3_f32 v96, v96, v120, v121
	v_fma_f32 v97, -v180, v97, v106
	v_cndmask_b32_e32 v122, v230, v97, vcc
	v_subrev_u32_e32 v97, 51, v171
	v_cmp_gt_u32_e32 vcc, s33, v97
	v_cvt_f32_i32_e32 v97, v97
	s_and_b64 vcc, vcc, s[36:37]
	v_fma_f32 v97, -v180, v97, v107
	v_cndmask_b32_e32 v123, v230, v97, vcc
	v_subrev_u32_e32 v97, 56, v171
	v_cmp_gt_u32_e32 vcc, s33, v97
	v_cvt_f32_i32_e32 v97, v97
	s_and_b64 vcc, vcc, s[36:37]
	v_max3_f32 v96, v96, v122, v123
	v_fma_f32 v97, -v180, v97, v108
	v_cndmask_b32_e32 v124, v230, v97, vcc
	v_subrev_u32_e32 v97, 57, v171
	v_cmp_gt_u32_e32 vcc, s33, v97
	v_cvt_f32_i32_e32 v97, v97
	s_and_b64 vcc, vcc, s[36:37]
	v_fma_f32 v97, -v180, v97, v109
	v_cndmask_b32_e32 v125, v230, v97, vcc
	v_subrev_u32_e32 v97, 58, v171
	v_cmp_gt_u32_e32 vcc, s33, v97
	v_cvt_f32_i32_e32 v97, v97
	s_and_b64 vcc, vcc, s[36:37]
	v_max3_f32 v96, v96, v124, v125
	v_fma_f32 v97, -v180, v97, v110
	v_cndmask_b32_e32 v126, v230, v97, vcc
	v_subrev_u32_e32 v97, 59, v171
	v_cmp_gt_u32_e32 vcc, s33, v97
	v_cvt_f32_i32_e32 v97, v97
	s_and_b64 vcc, vcc, s[36:37]
	v_fma_f32 v97, -v180, v97, v111
	v_cndmask_b32_e32 v127, v230, v97, vcc
	v_max3_f32 v96, v96, v126, v127
	v_mov_b32_e32 v97, v96
	s_nop 1
	v_permlane32_swap_b32_e32 v97, v96
	s_waitcnt lgkmcnt(0)
	v_max_f32_e32 v96, v96, v97
	v_add_f32_e32 v97, 0x41000000, v170
	v_cmp_gt_f32_e32 vcc, v96, v97
	s_cbranch_vccz .LBB0_635
; DI float fexp2(float x) { return __builtin_amdgcn_exp2f(x); }
; DI void softmax_step(int tid, int cls, f32x16 (&S)[2], f32x16 (&O)[2], float& m, float& l, int k0, int qpos, float slope2,
;                      int kmul, int kadd, int W, bool extra) {
;     ...
;       float mn = fmaxf(m, mx), alpha = fexp2(m - mn);
;       m = mn; l *= alpha;
; #pragma unroll
;       for (int dt = 0; dt < 2; ++dt)
; #pragma unroll
;         for (int i = 0; i < 16; ++i) O[dt][i] *= alpha;
	v_max_f32_e32 v96, v96, v96
	v_max_f32_e32 v97, v170, v170
	v_max_f32_e32 v97, v97, v96
	v_sub_f32_e32 v96, v170, v97
	v_exp_f32_e32 v96, v96
	v_mov_b32_e32 v170, v97
	v_mul_f32_e32 v214, v214, v96
	v_pk_mul_f32 v[78:79], v[78:79], v[96:97] op_sel_hi:[1,0]
	v_pk_mul_f32 v[76:77], v[76:77], v[96:97] op_sel_hi:[1,0]
	v_pk_mul_f32 v[74:75], v[74:75], v[96:97] op_sel_hi:[1,0]
	v_pk_mul_f32 v[72:73], v[72:73], v[96:97] op_sel_hi:[1,0]
	v_pk_mul_f32 v[70:71], v[70:71], v[96:97] op_sel_hi:[1,0]
	v_pk_mul_f32 v[68:69], v[68:69], v[96:97] op_sel_hi:[1,0]
	v_pk_mul_f32 v[66:67], v[66:67], v[96:97] op_sel_hi:[1,0]
	v_pk_mul_f32 v[64:65], v[64:65], v[96:97] op_sel_hi:[1,0]
	v_pk_mul_f32 v[62:63], v[62:63], v[96:97] op_sel_hi:[1,0]
	v_pk_mul_f32 v[60:61], v[60:61], v[96:97] op_sel_hi:[1,0]
	v_pk_mul_f32 v[58:59], v[58:59], v[96:97] op_sel_hi:[1,0]
	v_pk_mul_f32 v[56:57], v[56:57], v[96:97] op_sel_hi:[1,0]
	v_pk_mul_f32 v[54:55], v[54:55], v[96:97] op_sel_hi:[1,0]
	v_pk_mul_f32 v[52:53], v[52:53], v[96:97] op_sel_hi:[1,0]
	v_pk_mul_f32 v[50:51], v[50:51], v[96:97] op_sel_hi:[1,0]
	v_pk_mul_f32 v[48:49], v[48:49], v[96:97] op_sel_hi:[1,0]

; DI void softmax_step(int tid, int cls, f32x16 (&S)[2], f32x16 (&O)[2], float& m, float& l, int k0, int qpos, float slope2,
;                      int kmul, int kadd, int W, bool extra) {
;     ...
; #pragma unroll
;     for (int kt = 0; kt < 2; ++kt)
; #pragma unroll
;       for (int i = 0; i < 16; ++i) {
;         int d = dbase - (kt * 32 + (i & 3) + 8 * (i >> 2)) * kmul;
;         bool valid = extra && ((unsigned)d <= (unsigned)W);
;         float s2 = valid ? fmaf(-slope2, (float)d, S[kt][i]) : NEGB;
;         S[kt][i] = s2;
;         mx = fmaxf(mx, s2);
;       }
;     mx = fmaxf(mx, __shfl_xor(mx, 32));
;     if (__any(mx > m + 8.f)) {
.LBB0_665:
	s_andn2_saveexec_b64 s[6:7], s[0:1]
	s_cbranch_execz .LBB0_669
	v_cmp_gt_u32_e32 vcc, s33, v171
	s_and_b64 vcc, vcc, s[36:37]
	v_fma_f32 v80, -v180, v172, v128
	v_add_u32_e32 v81, -1, v171
	v_cndmask_b32_e32 v80, v230, v80, vcc
	v_cmp_gt_u32_e32 vcc, s33, v81
	v_cvt_f32_i32_e32 v81, v81
	s_and_b64 vcc, s[36:37], vcc
	v_add_u32_e32 v82, -2, v171
	v_add_u32_e32 v83, -3, v171
	v_fma_f32 v81, -v180, v81, v129
	v_cndmask_b32_e32 v81, v230, v81, vcc
	v_cmp_gt_u32_e32 vcc, s33, v82
	v_cvt_f32_i32_e32 v82, v82
	s_and_b64 vcc, s[36:37], vcc
	s_mov_b32 s0, 0xf149f2ca
	v_max3_f32 v84, v80, s0, v81
	v_fma_f32 v82, -v180, v82, v130
	v_cndmask_b32_e32 v82, v230, v82, vcc
	v_cmp_gt_u32_e32 vcc, s33, v83
	v_cvt_f32_i32_e32 v83, v83
	s_and_b64 vcc, vcc, s[36:37]
	v_add_u32_e32 v85, -9, v171
	v_add_u32_e32 v87, -11, v171
	v_fma_f32 v83, -v180, v83, v131
	v_cndmask_b32_e32 v83, v230, v83, vcc
	v_max3_f32 v86, v84, v82, v83
	v_add_u32_e32 v84, -8, v171
	v_cmp_gt_u32_e32 vcc, s33, v84
	v_cvt_f32_i32_e32 v84, v84
	s_and_b64 vcc, s[36:37], vcc
	v_subrev_u32_e32 v89, 17, v171
	v_subrev_u32_e32 v91, 19, v171
	v_fma_f32 v84, -v180, v84, v132
	v_cndmask_b32_e32 v84, v230, v84, vcc
	v_cmp_gt_u32_e32 vcc, s33, v85
	v_cvt_f32_i32_e32 v85, v85
	s_and_b64 vcc, vcc, s[36:37]
	v_subrev_u32_e32 v93, 25, v171
	v_subrev_u32_e32 v95, 27, v171
	v_fma_f32 v85, -v180, v85, v133
	v_cndmask_b32_e32 v85, v230, v85, vcc
	v_max3_f32 v88, v86, v84, v85
	v_add_u32_e32 v86, -10, v171
	v_cmp_gt_u32_e32 vcc, s33, v86
	v_cvt_f32_i32_e32 v86, v86
	s_and_b64 vcc, vcc, s[36:37]
	v_fma_f32 v86, -v180, v86, v134
	v_cndmask_b32_e32 v86, v230, v86, vcc
	v_cmp_gt_u32_e32 vcc, s33, v87
	v_cvt_f32_i32_e32 v87, v87
	s_and_b64 vcc, vcc, s[36:37]
	v_fma_f32 v87, -v180, v87, v135
	v_cndmask_b32_e32 v87, v230, v87, vcc
	v_max3_f32 v90, v88, v86, v87
	v_add_u32_e32 v88, -16, v171
	v_cmp_gt_u32_e32 vcc, s33, v88
	v_cvt_f32_i32_e32 v88, v88
	s_and_b64 vcc, s[36:37], vcc
	v_fma_f32 v88, -v180, v88, v136
	v_cndmask_b32_e32 v88, v230, v88, vcc
	v_cmp_gt_u32_e32 vcc, s33, v89
	v_cvt_f32_i32_e32 v89, v89
	s_and_b64 vcc, vcc, s[36:37]
	v_fma_f32 v89, -v180, v89, v137
	v_cndmask_b32_e32 v89, v230, v89, vcc
	v_max3_f32 v92, v90, v88, v89
	v_subrev_u32_e32 v90, 18, v171
	v_cmp_gt_u32_e32 vcc, s33, v90
	v_cvt_f32_i32_e32 v90, v90
	s_and_b64 vcc, vcc, s[36:37]
	v_fma_f32 v90, -v180, v90, v138
	v_cndmask_b32_e32 v90, v230, v90, vcc
	v_cmp_gt_u32_e32 vcc, s33, v91
	v_cvt_f32_i32_e32 v91, v91
	s_and_b64 vcc, vcc, s[36:37]
	v_fma_f32 v91, -v180, v91, v139
	v_cndmask_b32_e32 v91, v230, v91, vcc
	v_max3_f32 v94, v92, v90, v91
	v_subrev_u32_e32 v92, 24, v171
	v_cmp_gt_u32_e32 vcc, s33, v92
	v_cvt_f32_i32_e32 v92, v92
	s_and_b64 vcc, vcc, s[36:37]
	v_fma_f32 v92, -v180, v92, v140
	v_cndmask_b32_e32 v92, v230, v92, vcc
	v_cmp_gt_u32_e32 vcc, s33, v93
	v_cvt_f32_i32_e32 v93, v93
	s_and_b64 vcc, vcc, s[36:37]
	v_fma_f32 v93, -v180, v93, v141
	v_cndmask_b32_e32 v93, v230, v93, vcc
	v_max3_f32 v112, v94, v92, v93
	v_subrev_u32_e32 v94, 26, v171
	v_cmp_gt_u32_e32 vcc, s33, v94
	v_cvt_f32_i32_e32 v94, v94
	s_and_b64 vcc, vcc, s[36:37]
	v_fma_f32 v94, -v180, v94, v142
	v_cndmask_b32_e32 v94, v230, v94, vcc
	v_cmp_gt_u32_e32 vcc, s33, v95
	v_cvt_f32_i32_e32 v95, v95
	s_and_b64 vcc, vcc, s[36:37]
	v_fma_f32 v95, -v180, v95, v143
	v_cndmask_b32_e32 v95, v230, v95, vcc
	v_max3_f32 v114, v112, v94, v95
	v_subrev_u32_e32 v112, 32, v171
	v_cmp_gt_u32_e32 vcc, s33, v112
	v_cvt_f32_i32_e32 v112, v112
	s_and_b64 vcc, s[36:37], vcc
	v_fma_f32 v96, -v180, v112, v96
	v_cndmask_b32_e32 v112, v230, v96, vcc
	v_subrev_u32_e32 v96, 33, v171
	v_cmp_gt_u32_e32 vcc, s33, v96
	v_cvt_f32_i32_e32 v96, v96
	s_and_b64 vcc, vcc, s[36:37]
	v_fma_f32 v96, -v180, v96, v97
	v_subrev_u32_e32 v97, 34, v171
	v_cndmask_b32_e32 v113, v230, v96, vcc
	v_cmp_gt_u32_e32 vcc, s33, v97
	v_cvt_f32_i32_e32 v97, v97
	s_and_b64 vcc, vcc, s[36:37]
	v_max3_f32 v96, v114, v112, v113
	v_fma_f32 v97, -v180, v97, v98
	v_cndmask_b32_e32 v114, v230, v97, vcc
	v_subrev_u32_e32 v97, 35, v171
	v_cmp_gt_u32_e32 vcc, s33, v97
	v_cvt_f32_i32_e32 v97, v97
	s_and_b64 vcc, vcc, s[36:37]
	v_fma_f32 v97, -v180, v97, v99
	v_cndmask_b32_e32 v115, v230, v97, vcc
	v_subrev_u32_e32 v97, 40, v171
	v_cmp_gt_u32_e32 vcc, s33, v97
	v_cvt_f32_i32_e32 v97, v97
	s_and_b64 vcc, vcc, s[36:37]
	v_max3_f32 v96, v96, v114, v115
	v_fma_f32 v97, -v180, v97, v100
	v_cndmask_b32_e32 v116, v230, v97, vcc
	v_subrev_u32_e32 v97, 41, v171
	v_cmp_gt_u32_e32 vcc, s33, v97
	v_cvt_f32_i32_e32 v97, v97
	s_and_b64 vcc, vcc, s[36:37]
	v_fma_f32 v97, -v180, v97, v101
	v_cndmask_b32_e32 v117, v230, v97, vcc
	v_subrev_u32_e32 v97, 42, v171
	v_cmp_gt_u32_e32 vcc, s33, v97
	v_cvt_f32_i32_e32 v97, v97
	s_and_b64 vcc, vcc, s[36:37]
	v_max3_f32 v96, v96, v116, v117
	v_fma_f32 v97, -v180, v97, v102
	v_cndmask_b32_e32 v118, v230, v97, vcc
	v_subrev_u32_e32 v97, 43, v171
	v_cmp_gt_u32_e32 vcc, s33, v97
	v_cvt_f32_i32_e32 v97, v97
	s_and_b64 vcc, vcc, s[36:37]
	v_fma_f32 v97, -v180, v97, v103
	v_cndmask_b32_e32 v119, v230, v97, vcc
	v_subrev_u32_e32 v97, 48, v171
	v_cmp_gt_u32_e32 vcc, s33, v97
	v_cvt_f32_i32_e32 v97, v97
	s_and_b64 vcc, vcc, s[36:37]
	v_max3_f32 v96, v96, v118, v119
	v_fma_f32 v97, -v180, v97, v104
	v_cndmask_b32_e32 v120, v230, v97, vcc
	v_subrev_u32_e32 v97, 49, v171
	v_cmp_gt_u32_e32 vcc, s33, v97
	v_cvt_f32_i32_e32 v97, v97
	s_and_b64 vcc, vcc, s[36:37]
	v_fma_f32 v97, -v180, v97, v105
	v_cndmask_b32_e32 v121, v230, v97, vcc
	v_subrev_u32_e32 v97, 50, v171
	v_cmp_gt_u32_e32 vcc, s33, v97
	v_cvt_f32_i32_e32 v97, v97
	s_and_b64 vcc, vcc, s[36:37]
	v_max3_f32 v96, v96, v120, v121
	v_fma_f32 v97, -v180, v97, v106
	v_cndmask_b32_e32 v122, v230, v97, vcc
	v_subrev_u32_e32 v97, 51, v171
	v_cmp_gt_u32_e32 vcc, s33, v97
	v_cvt_f32_i32_e32 v97, v97
	s_and_b64 vcc, vcc, s[36:37]
	v_fma_f32 v97, -v180, v97, v107
	v_cndmask_b32_e32 v123, v230, v97, vcc
	v_subrev_u32_e32 v97, 56, v171
	v_cmp_gt_u32_e32 vcc, s33, v97
	v_cvt_f32_i32_e32 v97, v97
	s_and_b64 vcc, vcc, s[36:37]
	v_max3_f32 v96, v96, v122, v123
	v_fma_f32 v97, -v180, v97, v108
	v_cndmask_b32_e32 v124, v230, v97, vcc
	v_subrev_u32_e32 v97, 57, v171
	v_cmp_gt_u32_e32 vcc, s33, v97
	v_cvt_f32_i32_e32 v97, v97
	s_and_b64 vcc, vcc, s[36:37]
	v_fma_f32 v97, -v180, v97, v109
	v_cndmask_b32_e32 v125, v230, v97, vcc
	v_subrev_u32_e32 v97, 58, v171
	v_cmp_gt_u32_e32 vcc, s33, v97
	v_cvt_f32_i32_e32 v97, v97
	s_and_b64 vcc, vcc, s[36:37]
	v_max3_f32 v96, v96, v124, v125
	v_fma_f32 v97, -v180, v97, v110
	v_cndmask_b32_e32 v126, v230, v97, vcc
	v_subrev_u32_e32 v97, 59, v171
	v_cmp_gt_u32_e32 vcc, s33, v97
	v_cvt_f32_i32_e32 v97, v97
	s_and_b64 vcc, vcc, s[36:37]
	v_fma_f32 v97, -v180, v97, v111
	v_cndmask_b32_e32 v127, v230, v97, vcc
	v_max3_f32 v96, v96, v126, v127
	v_mov_b32_e32 v97, v96
	s_nop 1
	v_permlane32_swap_b32_e32 v97, v96
	s_waitcnt lgkmcnt(0)
	v_max_f32_e32 v96, v96, v97
	v_add_f32_e32 v97, 0x41000000, v170
	v_cmp_gt_f32_e32 vcc, v96, v97
	s_cbranch_vccz .LBB0_668
; DI float fexp2(float x) { return __builtin_amdgcn_exp2f(x); }
; DI void softmax_step(int tid, int cls, f32x16 (&S)[2], f32x16 (&O)[2], float& m, float& l, int k0, int qpos, float slope2,
;                      int kmul, int kadd, int W, bool extra) {
;     ...
;       float mn = fmaxf(m, mx), alpha = fexp2(m - mn);
;       m = mn; l *= alpha;
; #pragma unroll
;       for (int dt = 0; dt < 2; ++dt)
; #pragma unroll
;         for (int i = 0; i < 16; ++i) O[dt][i] *= alpha;
	v_max_f32_e32 v96, v96, v96
	v_max_f32_e32 v97, v170, v170
	v_max_f32_e32 v97, v97, v96
	v_sub_f32_e32 v96, v170, v97
	v_exp_f32_e32 v96, v96
	v_mov_b32_e32 v170, v97
	v_mul_f32_e32 v214, v214, v96
	v_pk_mul_f32 v[78:79], v[78:79], v[96:97] op_sel_hi:[1,0]
	v_pk_mul_f32 v[76:77], v[76:77], v[96:97] op_sel_hi:[1,0]
	v_pk_mul_f32 v[74:75], v[74:75], v[96:97] op_sel_hi:[1,0]
	v_pk_mul_f32 v[72:73], v[72:73], v[96:97] op_sel_hi:[1,0]
	v_pk_mul_f32 v[70:71], v[70:71], v[96:97] op_sel_hi:[1,0]
	v_pk_mul_f32 v[68:69], v[68:69], v[96:97] op_sel_hi:[1,0]
	v_pk_mul_f32 v[66:67], v[66:67], v[96:97] op_sel_hi:[1,0]
	v_pk_mul_f32 v[64:65], v[64:65], v[96:97] op_sel_hi:[1,0]
	v_pk_mul_f32 v[62:63], v[62:63], v[96:97] op_sel_hi:[1,0]
	v_pk_mul_f32 v[60:61], v[60:61], v[96:97] op_sel_hi:[1,0]
	v_pk_mul_f32 v[58:59], v[58:59], v[96:97] op_sel_hi:[1,0]
	v_pk_mul_f32 v[56:57], v[56:57], v[96:97] op_sel_hi:[1,0]
	v_pk_mul_f32 v[54:55], v[54:55], v[96:97] op_sel_hi:[1,0]
	v_pk_mul_f32 v[52:53], v[52:53], v[96:97] op_sel_hi:[1,0]
	v_pk_mul_f32 v[50:51], v[50:51], v[96:97] op_sel_hi:[1,0]
	v_pk_mul_f32 v[48:49], v[48:49], v[96:97] op_sel_hi:[1,0]

; DI float fexp2(float x) { return __builtin_amdgcn_exp2f(x); }
; DI void softmax_step(int tid, int cls, f32x16 (&S)[2], f32x16 (&O)[2], float& m, float& l, int k0, int qpos, float slope2,
;                      int kmul, int kadd, int W, bool extra) {
;     ...
;     mx += b0;
;     mx = fmaxf(mx, __shfl_xor(mx, 32));
;     if (__any(mx > m + 8.f)) {
;       float mn = fmaxf(m, mx), alpha = fexp2(m - mn);
;       m = mn; l *= alpha;
; #pragma unroll
;       for (int dt = 0; dt < 2; ++dt)
; #pragma unroll
;         for (int i = 0; i < 16; ++i) O[dt][i] *= alpha;
;     }
;     c = fmaxf(m, -1e20f) - b0;
.LBB0_704:
	s_or_b64 exec, exec, s[0:1]
	s_nop 0
	v_cvt_f32_i32_e32 v112, v220
	v_fma_f32 v113, -v180, v112, v221
	v_mov_b32_e32 v114, v113
	s_nop 1
	v_permlane32_swap_b32_e32 v114, v113
	s_waitcnt lgkmcnt(0)
	v_max_f32_e32 v113, v113, v114
	v_add_f32_e32 v114, 0x41000000, v219
	v_cmp_gt_f32_e32 vcc, v113, v114
	s_cbranch_vccz .LBB0_706
	v_max_f32_e32 v113, v113, v113
	v_max_f32_e32 v114, v219, v219
	v_max_f32_e32 v113, v114, v113
	v_sub_f32_e32 v114, v219, v113
	v_exp_f32_e32 v114, v114
	v_mov_b32_e32 v219, v113
	v_mul_f32_e32 v216, v216, v114
	v_pk_mul_f32 v[110:111], v[110:111], v[114:115] op_sel_hi:[1,0]
	v_pk_mul_f32 v[108:109], v[108:109], v[114:115] op_sel_hi:[1,0]
	v_pk_mul_f32 v[106:107], v[106:107], v[114:115] op_sel_hi:[1,0]
	v_pk_mul_f32 v[104:105], v[104:105], v[114:115] op_sel_hi:[1,0]
	v_pk_mul_f32 v[102:103], v[102:103], v[114:115] op_sel_hi:[1,0]
	v_pk_mul_f32 v[100:101], v[100:101], v[114:115] op_sel_hi:[1,0]
	v_pk_mul_f32 v[98:99], v[98:99], v[114:115] op_sel_hi:[1,0]
	v_pk_mul_f32 v[96:97], v[96:97], v[114:115] op_sel_hi:[1,0]
	v_pk_mul_f32 v[94:95], v[94:95], v[114:115] op_sel_hi:[1,0]
	v_pk_mul_f32 v[92:93], v[92:93], v[114:115] op_sel_hi:[1,0]
	v_pk_mul_f32 v[90:91], v[90:91], v[114:115] op_sel_hi:[1,0]
	v_pk_mul_f32 v[88:89], v[88:89], v[114:115] op_sel_hi:[1,0]
	v_pk_mul_f32 v[86:87], v[86:87], v[114:115] op_sel_hi:[1,0]
	v_pk_mul_f32 v[84:85], v[84:85], v[114:115] op_sel_hi:[1,0]
	v_pk_mul_f32 v[82:83], v[82:83], v[114:115] op_sel_hi:[1,0]
	v_pk_mul_f32 v[80:81], v[80:81], v[114:115] op_sel_hi:[1,0]

; DI void softmax_step(int tid, int cls, f32x16 (&S)[2], f32x16 (&O)[2], float& m, float& l, int k0, int qpos, float slope2,
;                      int kmul, int kadd, int W, bool extra) {
;     ...
; #pragma unroll
;     for (int kt = 0; kt < 2; ++kt)
; #pragma unroll
;       for (int i = 0; i < 16; ++i) {
;         int d = dbase - (kt * 32 + (i & 3) + 8 * (i >> 2)) * kmul;
;         bool valid = extra && ((unsigned)d <= (unsigned)W);
;         float s2 = valid ? fmaf(-slope2, (float)d, S[kt][i]) : NEGB;
;         S[kt][i] = s2;
;         mx = fmaxf(mx, s2);
;       }
;     mx = fmaxf(mx, __shfl_xor(mx, 32));
;     if (__any(mx > m + 8.f)) {
.LBB0_707:
	s_andn2_saveexec_b64 s[0:1], s[8:9]
	s_cbranch_execz .LBB0_711
	v_add_u32_e32 v0, 56, v222
	v_cvt_f32_i32_e32 v2, v220
	v_cvt_f32_i32_e32 v3, v0
	v_add_u32_e32 v6, -2, v220
	v_add_u32_e32 v7, -3, v220
	v_cvt_f32_i32_e32 v5, v7
	v_cvt_f32_i32_e32 v4, v6
	v_pk_fma_f32 v[2:3], v[182:183], v[2:3], v[128:129]
	v_cmp_gt_u32_e32 vcc, s12, v0
	v_add_u32_e32 v9, -8, v220
	s_mov_b32 s2, 0xf149f2ca
	v_cndmask_b32_e32 v189, v230, v3, vcc
	v_cmp_gt_u32_e32 vcc, s12, v220
	v_add_u32_e32 v10, -10, v220
	v_add_u32_e32 v11, -11, v220
	v_cndmask_b32_e32 v0, v230, v2, vcc
	v_cmp_gt_u32_e32 vcc, s12, v7
	v_add_u32_e32 v7, -9, v220
	v_pk_fma_f32 v[2:3], v[182:183], v[4:5], v[130:131]
	v_cvt_f32_i32_e32 v5, v7
	v_cvt_f32_i32_e32 v4, v9
	v_cndmask_b32_e32 v3, v230, v3, vcc
	v_cmp_gt_u32_e32 vcc, s12, v6
	v_max3_f32 v8, v0, s2, v189
	v_pk_fma_f32 v[4:5], v[182:183], v[4:5], v[132:133]
	v_cndmask_b32_e32 v2, v230, v2, vcc
	v_cmp_gt_u32_e32 vcc, s12, v7
	v_cvt_f32_i32_e32 v7, v11
	v_cvt_f32_i32_e32 v6, v10
	v_cndmask_b32_e32 v5, v230, v5, vcc
	v_cmp_gt_u32_e32 vcc, s12, v9
	v_max3_f32 v8, v8, v2, v3
	v_add_u32_e32 v13, -16, v220
	v_cndmask_b32_e32 v4, v230, v4, vcc
	v_cmp_gt_u32_e32 vcc, s12, v11
	v_subrev_u32_e32 v11, 17, v220
	v_max3_f32 v12, v8, v4, v5
	v_cvt_f32_i32_e32 v8, v13
	v_cvt_f32_i32_e32 v9, v11
	v_pk_fma_f32 v[6:7], v[182:183], v[6:7], v[134:135]
	v_subrev_u32_e32 v14, 18, v220
	v_cndmask_b32_e32 v7, v230, v7, vcc
	v_cmp_gt_u32_e32 vcc, s12, v10
	v_subrev_u32_e32 v15, 19, v220
	v_pk_fma_f32 v[8:9], v[182:183], v[8:9], v[136:137]
	v_cndmask_b32_e32 v6, v230, v6, vcc
	v_cmp_gt_u32_e32 vcc, s12, v11
	v_cvt_f32_i32_e32 v11, v15
	v_cvt_f32_i32_e32 v10, v14
	v_cndmask_b32_e32 v9, v230, v9, vcc
	v_cmp_gt_u32_e32 vcc, s12, v13
	v_max3_f32 v12, v12, v6, v7
	v_subrev_u32_e32 v129, 24, v220
	v_cndmask_b32_e32 v8, v230, v8, vcc
	v_cmp_gt_u32_e32 vcc, s12, v15
	v_subrev_u32_e32 v15, 25, v220
	v_max3_f32 v128, v12, v8, v9
	v_cvt_f32_i32_e32 v13, v15
	v_cvt_f32_i32_e32 v12, v129
	v_pk_fma_f32 v[10:11], v[182:183], v[10:11], v[138:139]
	v_subrev_u32_e32 v130, 26, v220
	v_cndmask_b32_e32 v11, v230, v11, vcc
	v_cmp_gt_u32_e32 vcc, s12, v14
	v_subrev_u32_e32 v131, 27, v220
	v_cvt_f32_i32_e32 v14, v130
	v_cndmask_b32_e32 v10, v230, v10, vcc
	v_cmp_gt_u32_e32 vcc, s12, v15
	v_cvt_f32_i32_e32 v15, v131
	v_pk_fma_f32 v[12:13], v[182:183], v[12:13], v[140:141]
	v_max3_f32 v128, v128, v10, v11
	v_cndmask_b32_e32 v13, v230, v13, vcc
	v_cmp_gt_u32_e32 vcc, s12, v129
	v_subrev_u32_e32 v133, 33, v220
	v_pk_fma_f32 v[14:15], v[182:183], v[14:15], v[142:143]
	v_cndmask_b32_e32 v12, v230, v12, vcc
	v_cmp_gt_u32_e32 vcc, s12, v131
	v_subrev_u32_e32 v131, 32, v220
	v_max3_f32 v132, v128, v12, v13
	v_cvt_f32_i32_e32 v129, v133
	v_cvt_f32_i32_e32 v128, v131
	v_cndmask_b32_e32 v15, v230, v15, vcc
	v_cmp_gt_u32_e32 vcc, s12, v130
	v_pk_fma_f32 v[112:113], v[182:183], v[128:129], v[112:113]
	s_nop 0
	v_cndmask_b32_e32 v14, v230, v14, vcc
	v_max3_f32 v130, v132, v14, v15
	v_cmp_gt_u32_e32 vcc, s12, v133
	v_subrev_u32_e32 v132, 34, v220
	v_subrev_u32_e32 v133, 35, v220
	v_cvt_f32_i32_e32 v129, v133
	v_cvt_f32_i32_e32 v128, v132
	v_cndmask_b32_e32 v191, v230, v113, vcc
	v_cmp_gt_u32_e32 vcc, s12, v131
	s_nop 1
	v_cndmask_b32_e32 v190, v230, v112, vcc
	v_pk_fma_f32 v[112:113], v[182:183], v[128:129], v[114:115]
	v_subrev_u32_e32 v128, 40, v220
	v_subrev_u32_e32 v129, 41, v220
	v_cvt_f32_i32_e32 v115, v129
	v_cvt_f32_i32_e32 v114, v128
	v_cmp_gt_u32_e32 vcc, s12, v133
	v_max3_f32 v130, v130, v190, v191
	s_nop 0
	v_cndmask_b32_e32 v193, v230, v113, vcc
	v_cmp_gt_u32_e32 vcc, s12, v132
	s_nop 1
	v_cndmask_b32_e32 v192, v230, v112, vcc
	v_pk_fma_f32 v[112:113], v[182:183], v[114:115], v[116:117]
	v_subrev_u32_e32 v116, 42, v220
	v_subrev_u32_e32 v117, 43, v220
	v_cvt_f32_i32_e32 v115, v117
	v_cvt_f32_i32_e32 v114, v116
	v_cmp_gt_u32_e32 vcc, s12, v129
	v_max3_f32 v130, v130, v192, v193
	s_nop 0
	v_cndmask_b32_e32 v195, v230, v113, vcc
	v_cmp_gt_u32_e32 vcc, s12, v128
	s_nop 1
	v_cndmask_b32_e32 v194, v230, v112, vcc
	v_pk_fma_f32 v[112:113], v[182:183], v[114:115], v[118:119]
	v_cmp_gt_u32_e32 vcc, s12, v117
	v_subrev_u32_e32 v117, 48, v220
	v_subrev_u32_e32 v118, 49, v220
	v_cvt_f32_i32_e32 v115, v118
	v_cvt_f32_i32_e32 v114, v117
	v_cndmask_b32_e32 v197, v230, v113, vcc
	v_cmp_gt_u32_e32 vcc, s12, v116
	v_subrev_u32_e32 v119, 51, v220
	v_max3_f32 v128, v130, v194, v195
	v_cndmask_b32_e32 v196, v230, v112, vcc
	v_cmp_gt_u32_e32 vcc, s12, v118
	v_subrev_u32_e32 v118, 50, v220
	v_pk_fma_f32 v[112:113], v[182:183], v[114:115], v[120:121]
	v_cvt_f32_i32_e32 v115, v119
	v_cvt_f32_i32_e32 v114, v118
	v_cndmask_b32_e32 v199, v230, v113, vcc
	v_cmp_gt_u32_e32 vcc, s12, v117
	v_subrev_u32_e32 v117, 56, v220
	v_max3_f32 v116, v128, v196, v197
	v_cndmask_b32_e32 v198, v230, v112, vcc
	v_cmp_gt_u32_e32 vcc, s12, v119
	v_subrev_u32_e32 v119, 57, v220
	v_pk_fma_f32 v[112:113], v[182:183], v[114:115], v[122:123]
	v_cvt_f32_i32_e32 v114, v117
	v_cvt_f32_i32_e32 v115, v119
	v_cndmask_b32_e32 v201, v230, v113, vcc
	v_cmp_gt_u32_e32 vcc, s12, v118
	v_subrev_u32_e32 v118, 58, v220
	v_max3_f32 v116, v116, v198, v199
	v_cndmask_b32_e32 v200, v230, v112, vcc
	v_cmp_gt_u32_e32 vcc, s12, v119
	v_subrev_u32_e32 v119, 59, v220
	v_pk_fma_f32 v[112:113], v[182:183], v[114:115], v[124:125]
	v_cvt_f32_i32_e32 v115, v119
	v_cvt_f32_i32_e32 v114, v118
	v_cndmask_b32_e32 v203, v230, v113, vcc
	v_cmp_gt_u32_e32 vcc, s12, v117
	v_max3_f32 v116, v116, v200, v201
	s_nop 0
	v_cndmask_b32_e32 v202, v230, v112, vcc
	v_pk_fma_f32 v[112:113], v[182:183], v[114:115], v[126:127]
	v_cmp_gt_u32_e32 vcc, s12, v119
	v_max3_f32 v116, v116, v202, v203
	s_nop 0
	v_cndmask_b32_e32 v205, v230, v113, vcc
	v_cmp_gt_u32_e32 vcc, s12, v118
	s_nop 1
	v_cndmask_b32_e32 v204, v230, v112, vcc
	v_max3_f32 v112, v116, v204, v205
	v_mov_b32_e32 v113, v112
	s_nop 1
	v_permlane32_swap_b32_e32 v113, v112
	s_waitcnt lgkmcnt(0)
	v_max_f32_e32 v112, v112, v113
	v_add_f32_e32 v113, 0x41000000, v219
	v_cmp_gt_f32_e32 vcc, v112, v113
	s_cbranch_vccz .LBB0_710
; DI float fexp2(float x) { return __builtin_amdgcn_exp2f(x); }
; DI void softmax_step(int tid, int cls, f32x16 (&S)[2], f32x16 (&O)[2], float& m, float& l, int k0, int qpos, float slope2,
;                      int kmul, int kadd, int W, bool extra) {
;     ...
;       float mn = fmaxf(m, mx), alpha = fexp2(m - mn);
;       m = mn; l *= alpha;
; #pragma unroll
;       for (int dt = 0; dt < 2; ++dt)
; #pragma unroll
;         for (int i = 0; i < 16; ++i) O[dt][i] *= alpha;
	v_max_f32_e32 v112, v112, v112
	v_max_f32_e32 v113, v219, v219
	v_max_f32_e32 v113, v113, v112
	v_sub_f32_e32 v112, v219, v113
	v_exp_f32_e32 v112, v112
	v_mov_b32_e32 v219, v113
	v_mul_f32_e32 v216, v216, v112
	v_pk_mul_f32 v[110:111], v[110:111], v[112:113] op_sel_hi:[1,0]
	v_pk_mul_f32 v[108:109], v[108:109], v[112:113] op_sel_hi:[1,0]
	v_pk_mul_f32 v[106:107], v[106:107], v[112:113] op_sel_hi:[1,0]
	v_pk_mul_f32 v[104:105], v[104:105], v[112:113] op_sel_hi:[1,0]
	v_pk_mul_f32 v[102:103], v[102:103], v[112:113] op_sel_hi:[1,0]
	v_pk_mul_f32 v[100:101], v[100:101], v[112:113] op_sel_hi:[1,0]
	v_pk_mul_f32 v[98:99], v[98:99], v[112:113] op_sel_hi:[1,0]
	v_pk_mul_f32 v[96:97], v[96:97], v[112:113] op_sel_hi:[1,0]
	v_pk_mul_f32 v[94:95], v[94:95], v[112:113] op_sel_hi:[1,0]
	v_pk_mul_f32 v[92:93], v[92:93], v[112:113] op_sel_hi:[1,0]
	v_pk_mul_f32 v[90:91], v[90:91], v[112:113] op_sel_hi:[1,0]
	v_pk_mul_f32 v[88:89], v[88:89], v[112:113] op_sel_hi:[1,0]
	v_pk_mul_f32 v[86:87], v[86:87], v[112:113] op_sel_hi:[1,0]
	v_pk_mul_f32 v[84:85], v[84:85], v[112:113] op_sel_hi:[1,0]
	v_pk_mul_f32 v[82:83], v[82:83], v[112:113] op_sel_hi:[1,0]
	v_pk_mul_f32 v[80:81], v[80:81], v[112:113] op_sel_hi:[1,0]

; DI void softmax_step(int tid, int cls, f32x16 (&S)[2], f32x16 (&O)[2], float& m, float& l, int k0, int qpos, float slope2,
;                      int kmul, int kadd, int W, bool extra) {
;     ...
; #pragma unroll
;     for (int kt = 0; kt < 2; ++kt)
; #pragma unroll
;       for (int i = 0; i < 16; ++i) {
;         int d = dbase - (kt * 32 + (i & 3) + 8 * (i >> 2)) * kmul;
;         bool valid = extra && ((unsigned)d <= (unsigned)W);
;         float s2 = valid ? fmaf(-slope2, (float)d, S[kt][i]) : NEGB;
;         S[kt][i] = s2;
;         mx = fmaxf(mx, s2);
;       }
;     mx = fmaxf(mx, __shfl_xor(mx, 32));
;     if (__any(mx > m + 8.f)) {
.LBB0_736:
	s_andn2_saveexec_b64 s[0:1], s[8:9]
	s_cbranch_execz .LBB0_740
	v_add_u32_e32 v0, -8, v222
	v_cvt_f32_i32_e32 v2, v220
	v_cvt_f32_i32_e32 v3, v0
	v_add_u32_e32 v6, -2, v220
	v_add_u32_e32 v7, -3, v220
	v_cvt_f32_i32_e32 v5, v7
	v_cvt_f32_i32_e32 v4, v6
	v_pk_fma_f32 v[2:3], v[182:183], v[2:3], v[128:129]
	v_cmp_gt_u32_e32 vcc, s12, v0
	v_add_u32_e32 v9, -8, v220
	s_mov_b32 s2, 0xf149f2ca
	v_cndmask_b32_e32 v189, v230, v3, vcc
	v_cmp_gt_u32_e32 vcc, s12, v220
	v_add_u32_e32 v10, -10, v220
	v_add_u32_e32 v11, -11, v220
	v_cndmask_b32_e32 v0, v230, v2, vcc
	v_cmp_gt_u32_e32 vcc, s12, v7
	v_add_u32_e32 v7, -9, v220
	v_pk_fma_f32 v[2:3], v[182:183], v[4:5], v[130:131]
	v_cvt_f32_i32_e32 v5, v7
	v_cvt_f32_i32_e32 v4, v9
	v_cndmask_b32_e32 v3, v230, v3, vcc
	v_cmp_gt_u32_e32 vcc, s12, v6
	v_max3_f32 v8, v0, s2, v189
	v_pk_fma_f32 v[4:5], v[182:183], v[4:5], v[132:133]
	v_cndmask_b32_e32 v2, v230, v2, vcc
	v_cmp_gt_u32_e32 vcc, s12, v7
	v_cvt_f32_i32_e32 v7, v11
	v_cvt_f32_i32_e32 v6, v10
	v_cndmask_b32_e32 v5, v230, v5, vcc
	v_cmp_gt_u32_e32 vcc, s12, v9
	v_max3_f32 v8, v8, v2, v3
	v_add_u32_e32 v13, -16, v220
	v_cndmask_b32_e32 v4, v230, v4, vcc
	v_cmp_gt_u32_e32 vcc, s12, v11
	v_subrev_u32_e32 v11, 17, v220
	v_max3_f32 v12, v8, v4, v5
	v_cvt_f32_i32_e32 v8, v13
	v_cvt_f32_i32_e32 v9, v11
	v_pk_fma_f32 v[6:7], v[182:183], v[6:7], v[134:135]
	v_subrev_u32_e32 v14, 18, v220
	v_cndmask_b32_e32 v7, v230, v7, vcc
	v_cmp_gt_u32_e32 vcc, s12, v10
	v_subrev_u32_e32 v15, 19, v220
	v_pk_fma_f32 v[8:9], v[182:183], v[8:9], v[136:137]
	v_cndmask_b32_e32 v6, v230, v6, vcc
	v_cmp_gt_u32_e32 vcc, s12, v11
	v_cvt_f32_i32_e32 v11, v15
	v_cvt_f32_i32_e32 v10, v14
	v_cndmask_b32_e32 v9, v230, v9, vcc
	v_cmp_gt_u32_e32 vcc, s12, v13
	v_max3_f32 v12, v12, v6, v7
	v_subrev_u32_e32 v129, 24, v220
	v_cndmask_b32_e32 v8, v230, v8, vcc
	v_cmp_gt_u32_e32 vcc, s12, v15
	v_subrev_u32_e32 v15, 25, v220
	v_max3_f32 v128, v12, v8, v9
	v_cvt_f32_i32_e32 v13, v15
	v_cvt_f32_i32_e32 v12, v129
	v_pk_fma_f32 v[10:11], v[182:183], v[10:11], v[138:139]
	v_subrev_u32_e32 v130, 26, v220
	v_cndmask_b32_e32 v11, v230, v11, vcc
	v_cmp_gt_u32_e32 vcc, s12, v14
	v_subrev_u32_e32 v131, 27, v220
	v_cvt_f32_i32_e32 v14, v130
	v_cndmask_b32_e32 v10, v230, v10, vcc
	v_cmp_gt_u32_e32 vcc, s12, v15
	v_cvt_f32_i32_e32 v15, v131
	v_pk_fma_f32 v[12:13], v[182:183], v[12:13], v[140:141]
	v_max3_f32 v128, v128, v10, v11
	v_cndmask_b32_e32 v13, v230, v13, vcc
	v_cmp_gt_u32_e32 vcc, s12, v129
	v_subrev_u32_e32 v133, 33, v220
	v_pk_fma_f32 v[14:15], v[182:183], v[14:15], v[142:143]
	v_cndmask_b32_e32 v12, v230, v12, vcc
	v_cmp_gt_u32_e32 vcc, s12, v131
	v_subrev_u32_e32 v131, 32, v220
	v_max3_f32 v132, v128, v12, v13
	v_cvt_f32_i32_e32 v129, v133
	v_cvt_f32_i32_e32 v128, v131
	v_cndmask_b32_e32 v15, v230, v15, vcc
	v_cmp_gt_u32_e32 vcc, s12, v130
	v_pk_fma_f32 v[112:113], v[182:183], v[128:129], v[112:113]
	s_nop 0
	v_cndmask_b32_e32 v14, v230, v14, vcc
	v_max3_f32 v130, v132, v14, v15
	v_cmp_gt_u32_e32 vcc, s12, v133
	v_subrev_u32_e32 v132, 34, v220
	v_subrev_u32_e32 v133, 35, v220
	v_cvt_f32_i32_e32 v129, v133
	v_cvt_f32_i32_e32 v128, v132
	v_cndmask_b32_e32 v191, v230, v113, vcc
	v_cmp_gt_u32_e32 vcc, s12, v131
	s_nop 1
	v_cndmask_b32_e32 v190, v230, v112, vcc
	v_pk_fma_f32 v[112:113], v[182:183], v[128:129], v[114:115]
	v_subrev_u32_e32 v128, 40, v220
	v_subrev_u32_e32 v129, 41, v220
	v_cvt_f32_i32_e32 v115, v129
	v_cvt_f32_i32_e32 v114, v128
	v_cmp_gt_u32_e32 vcc, s12, v133
	v_max3_f32 v130, v130, v190, v191
	s_nop 0
	v_cndmask_b32_e32 v193, v230, v113, vcc
	v_cmp_gt_u32_e32 vcc, s12, v132
	s_nop 1
	v_cndmask_b32_e32 v192, v230, v112, vcc
	v_pk_fma_f32 v[112:113], v[182:183], v[114:115], v[116:117]
	v_subrev_u32_e32 v116, 42, v220
	v_subrev_u32_e32 v117, 43, v220
	v_cvt_f32_i32_e32 v115, v117
	v_cvt_f32_i32_e32 v114, v116
	v_cmp_gt_u32_e32 vcc, s12, v129
	v_max3_f32 v130, v130, v192, v193
	s_nop 0
	v_cndmask_b32_e32 v195, v230, v113, vcc
	v_cmp_gt_u32_e32 vcc, s12, v128
	s_nop 1
	v_cndmask_b32_e32 v194, v230, v112, vcc
	v_pk_fma_f32 v[112:113], v[182:183], v[114:115], v[118:119]
	v_cmp_gt_u32_e32 vcc, s12, v117
	v_subrev_u32_e32 v117, 48, v220
	v_subrev_u32_e32 v118, 49, v220
	v_cvt_f32_i32_e32 v115, v118
	v_cvt_f32_i32_e32 v114, v117
	v_cndmask_b32_e32 v197, v230, v113, vcc
	v_cmp_gt_u32_e32 vcc, s12, v116
	v_subrev_u32_e32 v119, 51, v220
	v_max3_f32 v128, v130, v194, v195
	v_cndmask_b32_e32 v196, v230, v112, vcc
	v_cmp_gt_u32_e32 vcc, s12, v118
	v_subrev_u32_e32 v118, 50, v220
	v_pk_fma_f32 v[112:113], v[182:183], v[114:115], v[120:121]
	v_cvt_f32_i32_e32 v115, v119
	v_cvt_f32_i32_e32 v114, v118
	v_cndmask_b32_e32 v199, v230, v113, vcc
	v_cmp_gt_u32_e32 vcc, s12, v117
	v_subrev_u32_e32 v117, 56, v220
	v_max3_f32 v116, v128, v196, v197
	v_cndmask_b32_e32 v198, v230, v112, vcc
	v_cmp_gt_u32_e32 vcc, s12, v119
	v_subrev_u32_e32 v119, 57, v220
	v_pk_fma_f32 v[112:113], v[182:183], v[114:115], v[122:123]
	v_cvt_f32_i32_e32 v115, v119
	v_cvt_f32_i32_e32 v114, v117
	v_cndmask_b32_e32 v201, v230, v113, vcc
	v_cmp_gt_u32_e32 vcc, s12, v118
	v_subrev_u32_e32 v118, 58, v220
	v_max3_f32 v116, v116, v198, v199
	v_cndmask_b32_e32 v200, v230, v112, vcc
	v_cmp_gt_u32_e32 vcc, s12, v119
	v_subrev_u32_e32 v119, 59, v220
	v_pk_fma_f32 v[112:113], v[182:183], v[114:115], v[124:125]
	v_cvt_f32_i32_e32 v115, v119
	v_cvt_f32_i32_e32 v114, v118
	v_cndmask_b32_e32 v203, v230, v113, vcc
	v_cmp_gt_u32_e32 vcc, s12, v117
	v_max3_f32 v116, v116, v200, v201
	s_nop 0
	v_cndmask_b32_e32 v202, v230, v112, vcc
	v_pk_fma_f32 v[112:113], v[182:183], v[114:115], v[126:127]
	v_cmp_gt_u32_e32 vcc, s12, v119
	v_max3_f32 v116, v116, v202, v203
	s_nop 0
	v_cndmask_b32_e32 v205, v230, v113, vcc
	v_cmp_gt_u32_e32 vcc, s12, v118
	s_nop 1
	v_cndmask_b32_e32 v204, v230, v112, vcc
	v_max3_f32 v112, v116, v204, v205
	v_mov_b32_e32 v113, v112
	s_nop 1
	v_permlane32_swap_b32_e32 v113, v112
	s_waitcnt lgkmcnt(0)
	v_max_f32_e32 v112, v112, v113
	v_add_f32_e32 v113, 0x41000000, v219
	v_cmp_gt_f32_e32 vcc, v112, v113
	s_cbranch_vccz .LBB0_739
; DI float fexp2(float x) { return __builtin_amdgcn_exp2f(x); }
; DI void softmax_step(int tid, int cls, f32x16 (&S)[2], f32x16 (&O)[2], float& m, float& l, int k0, int qpos, float slope2,
;                      int kmul, int kadd, int W, bool extra) {
;     ...
;       float mn = fmaxf(m, mx), alpha = fexp2(m - mn);
;       m = mn; l *= alpha;
; #pragma unroll
;       for (int dt = 0; dt < 2; ++dt)
; #pragma unroll
;         for (int i = 0; i < 16; ++i) O[dt][i] *= alpha;
	v_max_f32_e32 v112, v112, v112
	v_max_f32_e32 v113, v219, v219
	v_max_f32_e32 v113, v113, v112
	v_sub_f32_e32 v112, v219, v113
	v_exp_f32_e32 v112, v112
	v_mov_b32_e32 v219, v113
	v_mul_f32_e32 v216, v216, v112
	v_pk_mul_f32 v[110:111], v[110:111], v[112:113] op_sel_hi:[1,0]
	v_pk_mul_f32 v[108:109], v[108:109], v[112:113] op_sel_hi:[1,0]
	v_pk_mul_f32 v[106:107], v[106:107], v[112:113] op_sel_hi:[1,0]
	v_pk_mul_f32 v[104:105], v[104:105], v[112:113] op_sel_hi:[1,0]
	v_pk_mul_f32 v[102:103], v[102:103], v[112:113] op_sel_hi:[1,0]
	v_pk_mul_f32 v[100:101], v[100:101], v[112:113] op_sel_hi:[1,0]
	v_pk_mul_f32 v[98:99], v[98:99], v[112:113] op_sel_hi:[1,0]
	v_pk_mul_f32 v[96:97], v[96:97], v[112:113] op_sel_hi:[1,0]
	v_pk_mul_f32 v[94:95], v[94:95], v[112:113] op_sel_hi:[1,0]
	v_pk_mul_f32 v[92:93], v[92:93], v[112:113] op_sel_hi:[1,0]
	v_pk_mul_f32 v[90:91], v[90:91], v[112:113] op_sel_hi:[1,0]
	v_pk_mul_f32 v[88:89], v[88:89], v[112:113] op_sel_hi:[1,0]
	v_pk_mul_f32 v[86:87], v[86:87], v[112:113] op_sel_hi:[1,0]
	v_pk_mul_f32 v[84:85], v[84:85], v[112:113] op_sel_hi:[1,0]
	v_pk_mul_f32 v[82:83], v[82:83], v[112:113] op_sel_hi:[1,0]
	v_pk_mul_f32 v[80:81], v[80:81], v[112:113] op_sel_hi:[1,0]
